# P5 onorm_pass: 8 rows unrolled, loads of 4 rows in flight (was 2 dependent round trips per row)
# speedup vs baseline: 1.0031x; 1.0031x over previous
; __device__ __forceinline__ float bflo(unsigned w) { return __uint_as_float(w << 16); }
; __device__ __forceinline__ float bfhi(unsigned w) { return __uint_as_float(w & 0xffff0000u); }
; __device__ __forceinline__ float rsq_f(float x) { return __builtin_amdgcn_rsqf(x); }
; __device__ __forceinline__ void onorm_pass(const float* obuf, const bf16_t* z, const float* ong, bf16_t* ycat, int gw, int NGW, int lane) {
;     ...
;     for (int row = gw; row < MP; row += NGW) {
;         const float* op = obuf + (size_t)row * 1024 + lane * 16; const bf16_t* zp = z + (size_t)row * NZ + 7168 + lane * 16;
;         f32x4 v[4]; float ss = 0.f;
; #pragma unroll
;         for (int i = 0; i < 4; ++i) { v[i] = *(const f32x4*)(op + 4 * i); ss += (v[i].x * v[i].x + v[i].y * v[i].y) + (v[i].z * v[i].z + v[i].w * v[i].w); }
;         const u32x4 g0 = *(const u32x4*)zp, g1 = *(const u32x4*)(zp + 8);
;         ss += __builtin_bit_cast(float, __builtin_amdgcn_update_dpp(0, __builtin_bit_cast(int, ss), 0xB1, 0xF, 0xF, true));
;         ss += __builtin_bit_cast(float, __builtin_amdgcn_update_dpp(0, __builtin_bit_cast(int, ss), 0x4E, 0xF, 0xF, true));
;         ss += __builtin_bit_cast(float, __builtin_amdgcn_update_dpp(0, __builtin_bit_cast(int, ss), 0x141, 0xF, 0xF, true));
;         const float rstd = rsq_f(ss * (1.f / HD) + EPS);
;         float y[16];
;         y[0] = v[0].x * rstd * g[0].x * silu_f(bflo(g0.x)); y[1] = v[0].y * rstd * g[0].y * silu_f(bfhi(g0.x)); y[2] = v[0].z * rstd * g[0].z * silu_f(bflo(g0.y)); y[3] = v[0].w * rstd * g[0].w * silu_f(bfhi(g0.y));
;         y[4] = v[1].x * rstd * g[1].x * silu_f(bflo(g0.z)); y[5] = v[1].y * rstd * g[1].y * silu_f(bfhi(g0.z)); y[6] = v[1].z * rstd * g[1].z * silu_f(bflo(g0.w)); y[7] = v[1].w * rstd * g[1].w * silu_f(bfhi(g0.w));
;         y[8] = v[2].x * rstd * g[2].x * silu_f(bflo(g1.x)); y[9] = v[2].y * rstd * g[2].y * silu_f(bfhi(g1.x)); y[10] = v[2].z * rstd * g[2].z * silu_f(bflo(g1.y)); y[11] = v[2].w * rstd * g[2].w * silu_f(bfhi(g1.y));
;         y[12] = v[3].x * rstd * g[3].x * silu_f(bflo(g1.z)); y[13] = v[3].y * rstd * g[3].y * silu_f(bfhi(g1.z)); y[14] = v[3].z * rstd * g[3].z * silu_f(bflo(g1.w)); y[15] = v[3].w * rstd * g[3].w * silu_f(bfhi(g1.w));
;         bf16_t* yp = ycat + (size_t)row * DM + 1024 + lane * 16;
;         *(u32x4*)yp = pack8(y); *(u32x4*)(yp + 8) = pack8(y + 8);
.LBB0_589:
	s_mov_b64 s[6:7], 0x13c03800
	v_lshl_add_u64 v[200:201], v[28:29], 0, v[50:51]
	v_lshl_add_u64 v[200:201], v[200:201], 0, s[8:9]
	v_lshl_add_u64 v[202:203], v[28:29], 0, v[48:49]
	v_lshl_add_u64 v[202:203], v[202:203], 0, s[6:7]
	global_load_dwordx4 v[68:71], v[200:201], off
	global_load_dwordx4 v[72:75], v[200:201], off offset:16
	global_load_dwordx4 v[76:79], v[200:201], off offset:32
	global_load_dwordx4 v[80:83], v[200:201], off offset:48
	global_load_dwordx4 v[84:87], v[202:203], off
	global_load_dwordx4 v[88:91], v[202:203], off offset:16
	v_lshl_add_u64 v[200:201], v[200:201], 0, s[84:85]
	v_lshl_add_u64 v[202:203], v[202:203], 0, s[60:61]
	global_load_dwordx4 v[92:95], v[200:201], off
	global_load_dwordx4 v[96:99], v[200:201], off offset:16
	global_load_dwordx4 v[100:103], v[200:201], off offset:32
	global_load_dwordx4 v[104:107], v[200:201], off offset:48
	global_load_dwordx4 v[108:111], v[202:203], off
	global_load_dwordx4 v[112:115], v[202:203], off offset:16
	v_lshl_add_u64 v[200:201], v[200:201], 0, s[84:85]
	v_lshl_add_u64 v[202:203], v[202:203], 0, s[60:61]
	global_load_dwordx4 v[116:119], v[200:201], off
	global_load_dwordx4 v[120:123], v[200:201], off offset:16
	global_load_dwordx4 v[124:127], v[200:201], off offset:32
	global_load_dwordx4 v[128:131], v[200:201], off offset:48
	global_load_dwordx4 v[132:135], v[202:203], off
	global_load_dwordx4 v[136:139], v[202:203], off offset:16
	v_lshl_add_u64 v[200:201], v[200:201], 0, s[84:85]
	v_lshl_add_u64 v[202:203], v[202:203], 0, s[60:61]
	global_load_dwordx4 v[140:143], v[200:201], off
	global_load_dwordx4 v[144:147], v[200:201], off offset:16
	global_load_dwordx4 v[148:151], v[200:201], off offset:32
	global_load_dwordx4 v[156:159], v[200:201], off offset:48
	global_load_dwordx4 v[160:163], v[202:203], off
	global_load_dwordx4 v[164:167], v[202:203], off offset:16
	v_lshl_add_u64 v[200:201], v[200:201], 0, s[84:85]
	v_lshl_add_u64 v[202:203], v[202:203], 0, s[60:61]
	v_lshl_add_u64 v[16:17], v[28:29], 0, v[50:51]
	v_lshl_add_u64 v[18:19], v[16:17], 0, s[8:9]
	v_add_co_u32_e32 v16, vcc, 0x28e00000, v16
	s_mov_b64 s[6:7], 0x13c03800
	s_nop 0
	v_addc_co_u32_e32 v17, vcc, 0, v17, vcc
	s_waitcnt vmcnt(18)
	v_mov_b32_e32 v52, v68
	v_mov_b32_e32 v53, v69
	v_mov_b32_e32 v54, v70
	v_mov_b32_e32 v55, v71
	v_mov_b32_e32 v20, v76
	v_mov_b32_e32 v21, v77
	v_mov_b32_e32 v22, v78
	v_mov_b32_e32 v23, v79
	v_mov_b32_e32 v24, v72
	v_mov_b32_e32 v25, v73
	v_mov_b32_e32 v26, v74
	v_mov_b32_e32 v27, v75
	s_nop 0
	v_mov_b32_e32 v16, v80
	v_mov_b32_e32 v17, v81
	v_mov_b32_e32 v18, v82
	v_mov_b32_e32 v19, v83
	s_mov_b32 s5, 0x20300000
	s_addk_i32 s4, 0x400
	v_lshl_add_u64 v[50:51], v[50:51], 0, s[84:85]
	s_cmpk_gt_i32 s4, 0x1bff
	s_nop 0
	v_pk_mul_f32 v[56:57], v[54:55], v[54:55]
	v_pk_mul_f32 v[58:59], v[52:53], v[52:53]
	s_nop 0
	v_mul_f32_e32 v0, v16, v16
	v_pk_mov_b32 v[60:61], v[58:59], v[56:57] op_sel:[1,0]
	v_mov_b32_e32 v59, v57
	v_pk_add_f32 v[56:57], v[60:61], v[58:59]
	v_pk_mul_f32 v[58:59], v[26:27], v[26:27]
	v_pk_mul_f32 v[60:61], v[24:25], v[24:25]
	v_mul_f32_e32 v2, v17, v17
	v_pk_mov_b32 v[62:63], v[60:61], v[58:59] op_sel:[1,0]
	v_mov_b32_e32 v61, v59
	v_pk_add_f32 v[58:59], v[62:63], v[60:61]
	v_pk_add_f32 v[56:57], v[56:57], v[56:57] op_sel:[0,1] op_sel_hi:[1,0]
	v_pk_add_f32 v[58:59], v[58:59], v[58:59] op_sel:[0,1] op_sel_hi:[1,0]
	v_mov_b32_e32 v57, v0
	v_mov_b32_e32 v59, v2
	v_mul_f32_e32 v0, v21, v21
	v_pk_add_f32 v[56:57], v[56:57], v[58:59]
	v_pk_fma_f32 v[58:59], v[20:21], v[20:21], v[0:1] op_sel_hi:[1,1,0]
	v_mul_f32_e32 v0, v23, v23
	v_mul_f32_e32 v4, v18, v18
	v_mul_f32_e32 v6, v19, v19
	v_pk_fma_f32 v[60:61], v[22:23], v[22:23], v[0:1] op_sel_hi:[1,1,0]
	v_mov_b32_e32 v59, v4
	v_mov_b32_e32 v61, v6
	v_pk_add_f32 v[58:59], v[58:59], v[60:61]
	s_nop 0
	v_pk_add_f32 v[56:57], v[56:57], v[58:59]
	s_nop 0
	v_add_f32_e32 v0, v56, v57
	v_lshl_add_u64 v[56:57], v[28:29], 0, v[48:49]
	v_lshl_add_u64 v[60:61], v[56:57], 0, s[6:7]
	v_add_co_u32_e32 v56, vcc, s76, v56
	v_add_f32_dpp v0, v0, v0 quad_perm:[1,0,3,2] row_mask:0xf bank_mask:0xf bound_ctrl:1
	s_nop 0
	v_addc_co_u32_e32 v57, vcc, 0, v57, vcc
	v_mov_b32_e32 v56, v84
	v_mov_b32_e32 v57, v85
	v_mov_b32_e32 v58, v86
	v_mov_b32_e32 v59, v87
	s_nop 0
	v_mov_b32_e32 v60, v88
	v_mov_b32_e32 v61, v89
	v_mov_b32_e32 v62, v90
	v_mov_b32_e32 v63, v91
	v_add_f32_dpp v0, v0, v0 quad_perm:[2,3,0,1] row_mask:0xf bank_mask:0xf bound_ctrl:1
	v_lshl_add_u64 v[48:49], v[48:49], 0, s[60:61]
	s_nop 0
	v_lshlrev_b32_e32 v64, 16, v56
	v_add_f32_dpp v0, v0, v0 row_half_mirror row_mask:0xf bank_mask:0xf bound_ctrl:1
	v_fmamk_f32 v0, v0, 0x3c000000, v194
	v_rsq_f32_e32 v6, v0
	v_mul_f32_e32 v0, 0xbfb8aa3b, v64
	v_exp_f32_e32 v0, v0
	v_mul_f32_e32 v65, v52, v6
	v_and_b32_e32 v52, 0xffff0000, v56
	v_add_f32_e32 v0, 1.0, v0
	v_rcp_f32_e32 v36, v0
	v_mul_f32_e32 v0, 0xbfb8aa3b, v52
	v_exp_f32_e32 v0, v0
	v_mul_f32_e32 v53, v53, v6
	v_mul_f32_e32 v21, v21, v6
	v_mul_f32_e32 v23, v23, v6
	v_add_f32_e32 v0, 1.0, v0
	v_rcp_f32_e32 v8, v0
	v_mul_f32_e32 v27, v27, v6
	v_mul_f32_e32 v19, v19, v6
	v_pk_mul_f32 v[64:65], v[36:37], v[64:65]
	v_pk_mul_f32 v[52:53], v[8:9], v[52:53]
	v_mul_f32_e32 v36, v64, v65
	v_mul_f32_e32 v8, v52, v53
	v_lshlrev_b32_e32 v52, 16, v57
	v_mul_f32_e32 v0, 0xbfb8aa3b, v52
	v_exp_f32_e32 v0, v0
	v_mul_f32_e32 v53, v54, v6
	v_add_f32_e32 v0, 1.0, v0
	v_rcp_f32_e32 v34, v0
	s_nop 0
	v_pk_mul_f32 v[52:53], v[34:35], v[52:53]
	s_nop 0
	v_mul_f32_e32 v34, v52, v53
	v_and_b32_e32 v52, 0xffff0000, v57
	v_mul_f32_e32 v0, 0xbfb8aa3b, v52
	v_exp_f32_e32 v0, v0
	v_mul_f32_e32 v53, v55, v6
	v_add_f32_e32 v0, 1.0, v0
; __device__ __forceinline__ float bflo(unsigned w) { return __uint_as_float(w << 16); }
; __device__ __forceinline__ float bfhi(unsigned w) { return __uint_as_float(w & 0xffff0000u); }
; __device__ __forceinline__ float silu_f(float x) { return x * rcp_f(1.f + exp_f(-x)); }
; __device__ __forceinline__ u32x4 pack8(const float* v) { u32x4 o; o.x = pk2(v[0], v[1]); o.y = pk2(v[2], v[3]); o.z = pk2(v[4], v[5]); o.w = pk2(v[6], v[7]); return o; }
; __device__ __forceinline__ void onorm_pass(const float* obuf, const bf16_t* z, const float* ong, bf16_t* ycat, int gw, int NGW, int lane) {
;     ...
;     for (int row = gw; row < MP; row += NGW) {
;         const float* op = obuf + (size_t)row * 1024 + lane * 16; const bf16_t* zp = z + (size_t)row * NZ + 7168 + lane * 16;
;         f32x4 v[4]; float ss = 0.f;
; #pragma unroll
;         for (int i = 0; i < 4; ++i) { v[i] = *(const f32x4*)(op + 4 * i); ss += (v[i].x * v[i].x + v[i].y * v[i].y) + (v[i].z * v[i].z + v[i].w * v[i].w); }
;         const u32x4 g0 = *(const u32x4*)zp, g1 = *(const u32x4*)(zp + 8);
;     ...
;         y[0] = v[0].x * rstd * g[0].x * silu_f(bflo(g0.x)); y[1] = v[0].y * rstd * g[0].y * silu_f(bfhi(g0.x)); y[2] = v[0].z * rstd * g[0].z * silu_f(bflo(g0.y)); y[3] = v[0].w * rstd * g[0].w * silu_f(bfhi(g0.y));
;         y[4] = v[1].x * rstd * g[1].x * silu_f(bflo(g0.z)); y[5] = v[1].y * rstd * g[1].y * silu_f(bfhi(g0.z)); y[6] = v[1].z * rstd * g[1].z * silu_f(bflo(g0.w)); y[7] = v[1].w * rstd * g[1].w * silu_f(bfhi(g0.w));
;         y[8] = v[2].x * rstd * g[2].x * silu_f(bflo(g1.x)); y[9] = v[2].y * rstd * g[2].y * silu_f(bfhi(g1.x)); y[10] = v[2].z * rstd * g[2].z * silu_f(bflo(g1.y)); y[11] = v[2].w * rstd * g[2].w * silu_f(bfhi(g1.y));
;         y[12] = v[3].x * rstd * g[3].x * silu_f(bflo(g1.z)); y[13] = v[3].y * rstd * g[3].y * silu_f(bfhi(g1.z)); y[14] = v[3].z * rstd * g[3].z * silu_f(bflo(g1.w)); y[15] = v[3].w * rstd * g[3].w * silu_f(bfhi(g1.w));
;         bf16_t* yp = ycat + (size_t)row * DM + 1024 + lane * 16;
;         *(u32x4*)yp = pack8(y); *(u32x4*)(yp + 8) = pack8(y + 8);
	v_rcp_f32_e32 v10, v0
	s_nop 0
	v_pk_mul_f32 v[52:53], v[10:11], v[52:53]
	s_nop 0
	v_mul_f32_e32 v10, v52, v53
	v_lshlrev_b32_e32 v52, 16, v58
	v_mul_f32_e32 v0, 0xbfb8aa3b, v52
	v_exp_f32_e32 v0, v0
	v_mul_f32_e32 v53, v24, v6
	v_add_f32_e32 v0, 1.0, v0
	v_rcp_f32_e32 v32, v0
	s_nop 0
	v_pk_mul_f32 v[52:53], v[32:33], v[52:53]
	s_nop 0
	v_mul_f32_e32 v24, v52, v53
	v_and_b32_e32 v52, 0xffff0000, v58
	v_mul_f32_e32 v0, 0xbfb8aa3b, v52
	v_exp_f32_e32 v0, v0
	v_mul_f32_e32 v53, v25, v6
	v_add_f32_e32 v0, 1.0, v0
	v_rcp_f32_e32 v12, v0
	s_nop 0
	v_pk_mul_f32 v[52:53], v[12:13], v[52:53]
	s_nop 0
	v_mul_f32_e32 v12, v52, v53
	v_lshlrev_b32_e32 v52, 16, v59
	v_mul_f32_e32 v0, 0xbfb8aa3b, v52
	v_exp_f32_e32 v0, v0
	v_mul_f32_e32 v53, v26, v6
	v_and_b32_e32 v26, 0xffff0000, v59
	v_cvt_pk_bf16_f32 v24, v24, v12
	v_add_f32_e32 v0, 1.0, v0
	v_rcp_f32_e32 v30, v0
	v_mul_f32_e32 v0, 0xbfb8aa3b, v26
	v_exp_f32_e32 v0, v0
	v_pk_mul_f32 v[52:53], v[30:31], v[52:53]
	s_nop 0
	v_mul_f32_e32 v25, v52, v53
	v_add_f32_e32 v0, 1.0, v0
	s_nop 0
	v_lshlrev_b32_e32 v52, 16, v60
	v_rcp_f32_e32 v14, v0
	v_mul_f32_e32 v0, 0xbfb8aa3b, v52
	v_exp_f32_e32 v0, v0
	v_mul_f32_e32 v53, v20, v6
	v_and_b32_e32 v20, 0xffff0000, v60
	v_pk_mul_f32 v[26:27], v[14:15], v[26:27]
	v_add_f32_e32 v0, 1.0, v0
	v_rcp_f32_e32 v44, v0
	v_mul_f32_e32 v0, 0xbfb8aa3b, v20
	v_exp_f32_e32 v0, v0
	v_mul_f32_e32 v26, v26, v27
	v_cvt_pk_bf16_f32 v25, v25, v26
	v_pk_mul_f32 v[52:53], v[44:45], v[52:53]
	v_add_f32_e32 v0, 1.0, v0
	v_rcp_f32_e32 v0, v0
	v_mul_f32_e32 v14, v52, v53
	v_pk_mul_f32 v[20:21], v[0:1], v[20:21]
	s_nop 0
	v_mul_f32_e32 v0, v20, v21
	v_lshlrev_b32_e32 v20, 16, v61
	v_mul_f32_e32 v2, 0xbfb8aa3b, v20
	v_exp_f32_e32 v2, v2
	v_mul_f32_e32 v21, v22, v6
	v_and_b32_e32 v22, 0xffff0000, v61
	v_add_f32_e32 v2, 1.0, v2
	v_rcp_f32_e32 v42, v2
	v_mul_f32_e32 v2, 0xbfb8aa3b, v22
	v_exp_f32_e32 v2, v2
	v_pk_mul_f32 v[20:21], v[42:43], v[20:21]
	s_nop 0
	v_mul_f32_e32 v20, v20, v21
	v_add_f32_e32 v2, 1.0, v2
	v_rcp_f32_e32 v2, v2
	s_nop 0
	v_pk_mul_f32 v[22:23], v[2:3], v[22:23]
	s_nop 0
	v_mul_f32_e32 v2, v22, v23
	v_lshlrev_b32_e32 v22, 16, v62
	v_mul_f32_e32 v4, 0xbfb8aa3b, v22
	v_exp_f32_e32 v4, v4
	v_mul_f32_e32 v23, v16, v6
	v_add_f32_e32 v4, 1.0, v4
	v_rcp_f32_e32 v40, v4
	s_nop 0
	v_pk_mul_f32 v[22:23], v[40:41], v[22:23]
	s_nop 0
	v_mul_f32_e32 v16, v22, v23
	v_and_b32_e32 v22, 0xffff0000, v62
	v_mul_f32_e32 v4, 0xbfb8aa3b, v22
	v_exp_f32_e32 v4, v4
	v_mul_f32_e32 v23, v17, v6
	v_add_f32_e32 v4, 1.0, v4
	v_rcp_f32_e32 v4, v4
	s_nop 0
	v_pk_mul_f32 v[22:23], v[4:5], v[22:23]
	s_nop 0
	v_mul_f32_e32 v4, v22, v23
	v_mul_f32_e32 v23, v18, v6
	v_and_b32_e32 v18, 0xffff0000, v63
	v_mul_f32_e32 v6, 0xbfb8aa3b, v18
	v_exp_f32_e32 v6, v6
	v_lshlrev_b32_e32 v22, 16, v63
	v_mul_f32_e32 v17, 0xbfb8aa3b, v22
	v_exp_f32_e32 v17, v17
	v_add_f32_e32 v6, 1.0, v6
	v_rcp_f32_e32 v6, v6
	v_add_f32_e32 v17, 1.0, v17
	v_rcp_f32_e32 v38, v17
	v_pk_mul_f32 v[18:19], v[6:7], v[18:19]
	v_pk_mul_f32 v[22:23], v[38:39], v[22:23]
	v_mul_f32_e32 v6, v18, v19
	v_lshl_add_u64 v[18:19], v[28:29], 0, v[46:47]
	v_add_co_u32_e32 v26, vcc, s5, v18
	v_lshl_add_u64 v[46:47], v[46:47], 0, s[84:85]
	s_nop 0
	v_addc_co_u32_e32 v27, vcc, 0, v19, vcc
	v_mul_f32_e32 v17, v22, v23
	v_cvt_pk_bf16_f32 v22, v36, v8
	v_cvt_pk_bf16_f32 v23, v34, v10
	global_store_dwordx4 v[26:27], v[22:25], off offset:2048
	v_cvt_pk_bf16_f32 v18, v14, v0
	v_cvt_pk_bf16_f32 v19, v20, v2
	v_cvt_pk_bf16_f32 v20, v16, v4
	v_cvt_pk_bf16_f32 v21, v17, v6
	global_store_dwordx4 v[26:27], v[18:21], off offset:2064
	global_load_dwordx4 v[68:71], v[200:201], off
	global_load_dwordx4 v[72:75], v[200:201], off offset:16
	global_load_dwordx4 v[76:79], v[200:201], off offset:32
	global_load_dwordx4 v[80:83], v[200:201], off offset:48
	global_load_dwordx4 v[84:87], v[202:203], off
	global_load_dwordx4 v[88:91], v[202:203], off offset:16
	v_lshl_add_u64 v[200:201], v[200:201], 0, s[84:85]
	v_lshl_add_u64 v[202:203], v[202:203], 0, s[60:61]
	v_lshl_add_u64 v[16:17], v[28:29], 0, v[50:51]
	v_lshl_add_u64 v[18:19], v[16:17], 0, s[8:9]
	v_add_co_u32_e32 v16, vcc, 0x28e00000, v16
	s_mov_b64 s[6:7], 0x13c03800
	s_nop 0
	v_addc_co_u32_e32 v17, vcc, 0, v17, vcc
	s_waitcnt vmcnt(20)
; __device__ __forceinline__ float bflo(unsigned w) { return __uint_as_float(w << 16); }
; __device__ __forceinline__ float bfhi(unsigned w) { return __uint_as_float(w & 0xffff0000u); }
; __device__ __forceinline__ float rsq_f(float x) { return __builtin_amdgcn_rsqf(x); }
; __device__ __forceinline__ void onorm_pass(const float* obuf, const bf16_t* z, const float* ong, bf16_t* ycat, int gw, int NGW, int lane) {
;     ...
;     for (int row = gw; row < MP; row += NGW) {
;         const float* op = obuf + (size_t)row * 1024 + lane * 16; const bf16_t* zp = z + (size_t)row * NZ + 7168 + lane * 16;
;         f32x4 v[4]; float ss = 0.f;
; #pragma unroll
;         for (int i = 0; i < 4; ++i) { v[i] = *(const f32x4*)(op + 4 * i); ss += (v[i].x * v[i].x + v[i].y * v[i].y) + (v[i].z * v[i].z + v[i].w * v[i].w); }
;         const u32x4 g0 = *(const u32x4*)zp, g1 = *(const u32x4*)(zp + 8);
;         ss += __builtin_bit_cast(float, __builtin_amdgcn_update_dpp(0, __builtin_bit_cast(int, ss), 0xB1, 0xF, 0xF, true));
;         ss += __builtin_bit_cast(float, __builtin_amdgcn_update_dpp(0, __builtin_bit_cast(int, ss), 0x4E, 0xF, 0xF, true));
;         ss += __builtin_bit_cast(float, __builtin_amdgcn_update_dpp(0, __builtin_bit_cast(int, ss), 0x141, 0xF, 0xF, true));
;         const float rstd = rsq_f(ss * (1.f / HD) + EPS);
;         float y[16];
;         y[0] = v[0].x * rstd * g[0].x * silu_f(bflo(g0.x)); y[1] = v[0].y * rstd * g[0].y * silu_f(bfhi(g0.x)); y[2] = v[0].z * rstd * g[0].z * silu_f(bflo(g0.y)); y[3] = v[0].w * rstd * g[0].w * silu_f(bfhi(g0.y));
;         y[4] = v[1].x * rstd * g[1].x * silu_f(bflo(g0.z)); y[5] = v[1].y * rstd * g[1].y * silu_f(bfhi(g0.z)); y[6] = v[1].z * rstd * g[1].z * silu_f(bflo(g0.w)); y[7] = v[1].w * rstd * g[1].w * silu_f(bfhi(g0.w));
;         y[8] = v[2].x * rstd * g[2].x * silu_f(bflo(g1.x)); y[9] = v[2].y * rstd * g[2].y * silu_f(bfhi(g1.x)); y[10] = v[2].z * rstd * g[2].z * silu_f(bflo(g1.y)); y[11] = v[2].w * rstd * g[2].w * silu_f(bfhi(g1.y));
;         y[12] = v[3].x * rstd * g[3].x * silu_f(bflo(g1.z)); y[13] = v[3].y * rstd * g[3].y * silu_f(bfhi(g1.z)); y[14] = v[3].z * rstd * g[3].z * silu_f(bflo(g1.w)); y[15] = v[3].w * rstd * g[3].w * silu_f(bfhi(g1.w));
;         bf16_t* yp = ycat + (size_t)row * DM + 1024 + lane * 16;
;         *(u32x4*)yp = pack8(y); *(u32x4*)(yp + 8) = pack8(y + 8);
	v_mov_b32_e32 v52, v92
	v_mov_b32_e32 v53, v93
	v_mov_b32_e32 v54, v94
	v_mov_b32_e32 v55, v95
	v_mov_b32_e32 v20, v100
	v_mov_b32_e32 v21, v101
	v_mov_b32_e32 v22, v102
	v_mov_b32_e32 v23, v103
	v_mov_b32_e32 v24, v96
	v_mov_b32_e32 v25, v97
	v_mov_b32_e32 v26, v98
	v_mov_b32_e32 v27, v99
	s_nop 0
	v_mov_b32_e32 v16, v104
	v_mov_b32_e32 v17, v105
	v_mov_b32_e32 v18, v106
	v_mov_b32_e32 v19, v107
	s_mov_b32 s5, 0x20300000
	s_addk_i32 s4, 0x400
	v_lshl_add_u64 v[50:51], v[50:51], 0, s[84:85]
	s_cmpk_gt_i32 s4, 0x1bff
	s_nop 0
	v_pk_mul_f32 v[56:57], v[54:55], v[54:55]
	v_pk_mul_f32 v[58:59], v[52:53], v[52:53]
	s_nop 0
	v_mul_f32_e32 v0, v16, v16
	v_pk_mov_b32 v[60:61], v[58:59], v[56:57] op_sel:[1,0]
	v_mov_b32_e32 v59, v57
	v_pk_add_f32 v[56:57], v[60:61], v[58:59]
	v_pk_mul_f32 v[58:59], v[26:27], v[26:27]
	v_pk_mul_f32 v[60:61], v[24:25], v[24:25]
	v_mul_f32_e32 v2, v17, v17
	v_pk_mov_b32 v[62:63], v[60:61], v[58:59] op_sel:[1,0]
	v_mov_b32_e32 v61, v59
	v_pk_add_f32 v[58:59], v[62:63], v[60:61]
	v_pk_add_f32 v[56:57], v[56:57], v[56:57] op_sel:[0,1] op_sel_hi:[1,0]
	v_pk_add_f32 v[58:59], v[58:59], v[58:59] op_sel:[0,1] op_sel_hi:[1,0]
	v_mov_b32_e32 v57, v0
	v_mov_b32_e32 v59, v2
	v_mul_f32_e32 v0, v21, v21
	v_pk_add_f32 v[56:57], v[56:57], v[58:59]
	v_pk_fma_f32 v[58:59], v[20:21], v[20:21], v[0:1] op_sel_hi:[1,1,0]
	v_mul_f32_e32 v0, v23, v23
	v_mul_f32_e32 v4, v18, v18
	v_mul_f32_e32 v6, v19, v19
	v_pk_fma_f32 v[60:61], v[22:23], v[22:23], v[0:1] op_sel_hi:[1,1,0]
	v_mov_b32_e32 v59, v4
	v_mov_b32_e32 v61, v6
	v_pk_add_f32 v[58:59], v[58:59], v[60:61]
	s_nop 0
	v_pk_add_f32 v[56:57], v[56:57], v[58:59]
	s_nop 0
	v_add_f32_e32 v0, v56, v57
	v_lshl_add_u64 v[56:57], v[28:29], 0, v[48:49]
	v_lshl_add_u64 v[60:61], v[56:57], 0, s[6:7]
	v_add_co_u32_e32 v56, vcc, s76, v56
	v_add_f32_dpp v0, v0, v0 quad_perm:[1,0,3,2] row_mask:0xf bank_mask:0xf bound_ctrl:1
	s_nop 0
	v_addc_co_u32_e32 v57, vcc, 0, v57, vcc
	v_mov_b32_e32 v56, v108
	v_mov_b32_e32 v57, v109
	v_mov_b32_e32 v58, v110
	v_mov_b32_e32 v59, v111
	s_nop 0
	v_mov_b32_e32 v60, v112
	v_mov_b32_e32 v61, v113
	v_mov_b32_e32 v62, v114
	v_mov_b32_e32 v63, v115
	v_add_f32_dpp v0, v0, v0 quad_perm:[2,3,0,1] row_mask:0xf bank_mask:0xf bound_ctrl:1
	v_lshl_add_u64 v[48:49], v[48:49], 0, s[60:61]
	s_nop 0
	v_lshlrev_b32_e32 v64, 16, v56
	v_add_f32_dpp v0, v0, v0 row_half_mirror row_mask:0xf bank_mask:0xf bound_ctrl:1
	v_fmamk_f32 v0, v0, 0x3c000000, v194
	v_rsq_f32_e32 v6, v0
	v_mul_f32_e32 v0, 0xbfb8aa3b, v64
	v_exp_f32_e32 v0, v0
	v_mul_f32_e32 v65, v52, v6
	v_and_b32_e32 v52, 0xffff0000, v56
	v_add_f32_e32 v0, 1.0, v0
	v_rcp_f32_e32 v36, v0
	v_mul_f32_e32 v0, 0xbfb8aa3b, v52
	v_exp_f32_e32 v0, v0
	v_mul_f32_e32 v53, v53, v6
	v_mul_f32_e32 v21, v21, v6
	v_mul_f32_e32 v23, v23, v6
	v_add_f32_e32 v0, 1.0, v0
	v_rcp_f32_e32 v8, v0
	v_mul_f32_e32 v27, v27, v6
	v_mul_f32_e32 v19, v19, v6
	v_pk_mul_f32 v[64:65], v[36:37], v[64:65]
	v_pk_mul_f32 v[52:53], v[8:9], v[52:53]
	v_mul_f32_e32 v36, v64, v65
	v_mul_f32_e32 v8, v52, v53
	v_lshlrev_b32_e32 v52, 16, v57
	v_mul_f32_e32 v0, 0xbfb8aa3b, v52
	v_exp_f32_e32 v0, v0
	v_mul_f32_e32 v53, v54, v6
	v_add_f32_e32 v0, 1.0, v0
	v_rcp_f32_e32 v34, v0
	s_nop 0
	v_pk_mul_f32 v[52:53], v[34:35], v[52:53]
	s_nop 0
	v_mul_f32_e32 v34, v52, v53
	v_and_b32_e32 v52, 0xffff0000, v57
	v_mul_f32_e32 v0, 0xbfb8aa3b, v52
	v_exp_f32_e32 v0, v0
	v_mul_f32_e32 v53, v55, v6
	v_add_f32_e32 v0, 1.0, v0
	v_rcp_f32_e32 v10, v0
	s_nop 0
	v_pk_mul_f32 v[52:53], v[10:11], v[52:53]
	s_nop 0
	v_mul_f32_e32 v10, v52, v53
	v_lshlrev_b32_e32 v52, 16, v58
	v_mul_f32_e32 v0, 0xbfb8aa3b, v52
	v_exp_f32_e32 v0, v0
	v_mul_f32_e32 v53, v24, v6
	v_add_f32_e32 v0, 1.0, v0
	v_rcp_f32_e32 v32, v0
	s_nop 0
	v_pk_mul_f32 v[52:53], v[32:33], v[52:53]
	s_nop 0
	v_mul_f32_e32 v24, v52, v53
	v_and_b32_e32 v52, 0xffff0000, v58
	v_mul_f32_e32 v0, 0xbfb8aa3b, v52
	v_exp_f32_e32 v0, v0
	v_mul_f32_e32 v53, v25, v6
	v_add_f32_e32 v0, 1.0, v0
	v_rcp_f32_e32 v12, v0
	s_nop 0
	v_pk_mul_f32 v[52:53], v[12:13], v[52:53]
	s_nop 0
	v_mul_f32_e32 v12, v52, v53
	v_lshlrev_b32_e32 v52, 16, v59
	v_mul_f32_e32 v0, 0xbfb8aa3b, v52
	v_exp_f32_e32 v0, v0
	v_mul_f32_e32 v53, v26, v6
	v_and_b32_e32 v26, 0xffff0000, v59
	v_cvt_pk_bf16_f32 v24, v24, v12
	v_add_f32_e32 v0, 1.0, v0
	v_rcp_f32_e32 v30, v0
	v_mul_f32_e32 v0, 0xbfb8aa3b, v26
	v_exp_f32_e32 v0, v0
	v_pk_mul_f32 v[52:53], v[30:31], v[52:53]
	s_nop 0
	v_mul_f32_e32 v25, v52, v53
	v_add_f32_e32 v0, 1.0, v0
	s_nop 0
	v_lshlrev_b32_e32 v52, 16, v60
	v_rcp_f32_e32 v14, v0
	v_mul_f32_e32 v0, 0xbfb8aa3b, v52
	v_exp_f32_e32 v0, v0
	v_mul_f32_e32 v53, v20, v6
	v_and_b32_e32 v20, 0xffff0000, v60
	v_pk_mul_f32 v[26:27], v[14:15], v[26:27]
	v_add_f32_e32 v0, 1.0, v0
	v_rcp_f32_e32 v44, v0
	v_mul_f32_e32 v0, 0xbfb8aa3b, v20
	v_exp_f32_e32 v0, v0
	v_mul_f32_e32 v26, v26, v27
	v_cvt_pk_bf16_f32 v25, v25, v26
	v_pk_mul_f32 v[52:53], v[44:45], v[52:53]
	v_add_f32_e32 v0, 1.0, v0
	v_rcp_f32_e32 v0, v0
	v_mul_f32_e32 v14, v52, v53
	v_pk_mul_f32 v[20:21], v[0:1], v[20:21]
	s_nop 0
	v_mul_f32_e32 v0, v20, v21
	v_lshlrev_b32_e32 v20, 16, v61
	v_mul_f32_e32 v2, 0xbfb8aa3b, v20
	v_exp_f32_e32 v2, v2
	v_mul_f32_e32 v21, v22, v6
	v_and_b32_e32 v22, 0xffff0000, v61
	v_add_f32_e32 v2, 1.0, v2
	v_rcp_f32_e32 v42, v2
	v_mul_f32_e32 v2, 0xbfb8aa3b, v22
	v_exp_f32_e32 v2, v2
	v_pk_mul_f32 v[20:21], v[42:43], v[20:21]
	s_nop 0
	v_mul_f32_e32 v20, v20, v21
	v_add_f32_e32 v2, 1.0, v2
	v_rcp_f32_e32 v2, v2
	s_nop 0
	v_pk_mul_f32 v[22:23], v[2:3], v[22:23]
	s_nop 0
	v_mul_f32_e32 v2, v22, v23
	v_lshlrev_b32_e32 v22, 16, v62
	v_mul_f32_e32 v4, 0xbfb8aa3b, v22
	v_exp_f32_e32 v4, v4
; __device__ __forceinline__ float bflo(unsigned w) { return __uint_as_float(w << 16); }
; __device__ __forceinline__ float bfhi(unsigned w) { return __uint_as_float(w & 0xffff0000u); }
; __device__ __forceinline__ float rsq_f(float x) { return __builtin_amdgcn_rsqf(x); }
; __device__ __forceinline__ void onorm_pass(const float* obuf, const bf16_t* z, const float* ong, bf16_t* ycat, int gw, int NGW, int lane) {
;     ...
;     for (int row = gw; row < MP; row += NGW) {
;         const float* op = obuf + (size_t)row * 1024 + lane * 16; const bf16_t* zp = z + (size_t)row * NZ + 7168 + lane * 16;
;         f32x4 v[4]; float ss = 0.f;
; #pragma unroll
;         for (int i = 0; i < 4; ++i) { v[i] = *(const f32x4*)(op + 4 * i); ss += (v[i].x * v[i].x + v[i].y * v[i].y) + (v[i].z * v[i].z + v[i].w * v[i].w); }
;         const u32x4 g0 = *(const u32x4*)zp, g1 = *(const u32x4*)(zp + 8);
;         ss += __builtin_bit_cast(float, __builtin_amdgcn_update_dpp(0, __builtin_bit_cast(int, ss), 0xB1, 0xF, 0xF, true));
;         ss += __builtin_bit_cast(float, __builtin_amdgcn_update_dpp(0, __builtin_bit_cast(int, ss), 0x4E, 0xF, 0xF, true));
;         ss += __builtin_bit_cast(float, __builtin_amdgcn_update_dpp(0, __builtin_bit_cast(int, ss), 0x141, 0xF, 0xF, true));
;         const float rstd = rsq_f(ss * (1.f / HD) + EPS);
;         float y[16];
;         y[0] = v[0].x * rstd * g[0].x * silu_f(bflo(g0.x)); y[1] = v[0].y * rstd * g[0].y * silu_f(bfhi(g0.x)); y[2] = v[0].z * rstd * g[0].z * silu_f(bflo(g0.y)); y[3] = v[0].w * rstd * g[0].w * silu_f(bfhi(g0.y));
;         y[4] = v[1].x * rstd * g[1].x * silu_f(bflo(g0.z)); y[5] = v[1].y * rstd * g[1].y * silu_f(bfhi(g0.z)); y[6] = v[1].z * rstd * g[1].z * silu_f(bflo(g0.w)); y[7] = v[1].w * rstd * g[1].w * silu_f(bfhi(g0.w));
;         y[8] = v[2].x * rstd * g[2].x * silu_f(bflo(g1.x)); y[9] = v[2].y * rstd * g[2].y * silu_f(bfhi(g1.x)); y[10] = v[2].z * rstd * g[2].z * silu_f(bflo(g1.y)); y[11] = v[2].w * rstd * g[2].w * silu_f(bfhi(g1.y));
;         y[12] = v[3].x * rstd * g[3].x * silu_f(bflo(g1.z)); y[13] = v[3].y * rstd * g[3].y * silu_f(bfhi(g1.z)); y[14] = v[3].z * rstd * g[3].z * silu_f(bflo(g1.w)); y[15] = v[3].w * rstd * g[3].w * silu_f(bfhi(g1.w));
;         bf16_t* yp = ycat + (size_t)row * DM + 1024 + lane * 16;
;         *(u32x4*)yp = pack8(y); *(u32x4*)(yp + 8) = pack8(y + 8);
	v_mul_f32_e32 v23, v16, v6
	v_add_f32_e32 v4, 1.0, v4
	v_rcp_f32_e32 v40, v4
	s_nop 0
	v_pk_mul_f32 v[22:23], v[40:41], v[22:23]
	s_nop 0
	v_mul_f32_e32 v16, v22, v23
	v_and_b32_e32 v22, 0xffff0000, v62
	v_mul_f32_e32 v4, 0xbfb8aa3b, v22
	v_exp_f32_e32 v4, v4
	v_mul_f32_e32 v23, v17, v6
	v_add_f32_e32 v4, 1.0, v4
	v_rcp_f32_e32 v4, v4
	s_nop 0
	v_pk_mul_f32 v[22:23], v[4:5], v[22:23]
	s_nop 0
	v_mul_f32_e32 v4, v22, v23
	v_mul_f32_e32 v23, v18, v6
	v_and_b32_e32 v18, 0xffff0000, v63
	v_mul_f32_e32 v6, 0xbfb8aa3b, v18
	v_exp_f32_e32 v6, v6
	v_lshlrev_b32_e32 v22, 16, v63
	v_mul_f32_e32 v17, 0xbfb8aa3b, v22
	v_exp_f32_e32 v17, v17
	v_add_f32_e32 v6, 1.0, v6
	v_rcp_f32_e32 v6, v6
	v_add_f32_e32 v17, 1.0, v17
	v_rcp_f32_e32 v38, v17
	v_pk_mul_f32 v[18:19], v[6:7], v[18:19]
	v_pk_mul_f32 v[22:23], v[38:39], v[22:23]
	v_mul_f32_e32 v6, v18, v19
	v_lshl_add_u64 v[18:19], v[28:29], 0, v[46:47]
	v_add_co_u32_e32 v26, vcc, s5, v18
	v_lshl_add_u64 v[46:47], v[46:47], 0, s[84:85]
	s_nop 0
	v_addc_co_u32_e32 v27, vcc, 0, v19, vcc
	v_mul_f32_e32 v17, v22, v23
	v_cvt_pk_bf16_f32 v22, v36, v8
	v_cvt_pk_bf16_f32 v23, v34, v10
	global_store_dwordx4 v[26:27], v[22:25], off offset:2048
	v_cvt_pk_bf16_f32 v18, v14, v0
	v_cvt_pk_bf16_f32 v19, v20, v2
	v_cvt_pk_bf16_f32 v20, v16, v4
	v_cvt_pk_bf16_f32 v21, v17, v6
	global_store_dwordx4 v[26:27], v[18:21], off offset:2064
	global_load_dwordx4 v[92:95], v[200:201], off
	global_load_dwordx4 v[96:99], v[200:201], off offset:16
	global_load_dwordx4 v[100:103], v[200:201], off offset:32
	global_load_dwordx4 v[104:107], v[200:201], off offset:48
	global_load_dwordx4 v[108:111], v[202:203], off
	global_load_dwordx4 v[112:115], v[202:203], off offset:16
	v_lshl_add_u64 v[200:201], v[200:201], 0, s[84:85]
	v_lshl_add_u64 v[202:203], v[202:203], 0, s[60:61]
	v_lshl_add_u64 v[16:17], v[28:29], 0, v[50:51]
	v_lshl_add_u64 v[18:19], v[16:17], 0, s[8:9]
	v_add_co_u32_e32 v16, vcc, 0x28e00000, v16
	s_mov_b64 s[6:7], 0x13c03800
	s_nop 0
	v_addc_co_u32_e32 v17, vcc, 0, v17, vcc
	s_waitcnt vmcnt(22)
	v_mov_b32_e32 v52, v116
	v_mov_b32_e32 v53, v117
	v_mov_b32_e32 v54, v118
	v_mov_b32_e32 v55, v119
	v_mov_b32_e32 v20, v124
	v_mov_b32_e32 v21, v125
	v_mov_b32_e32 v22, v126
	v_mov_b32_e32 v23, v127
	v_mov_b32_e32 v24, v120
	v_mov_b32_e32 v25, v121
	v_mov_b32_e32 v26, v122
	v_mov_b32_e32 v27, v123
	s_nop 0
	v_mov_b32_e32 v16, v128
	v_mov_b32_e32 v17, v129
	v_mov_b32_e32 v18, v130
	v_mov_b32_e32 v19, v131
	s_mov_b32 s5, 0x20300000
	s_addk_i32 s4, 0x400
	v_lshl_add_u64 v[50:51], v[50:51], 0, s[84:85]
	s_cmpk_gt_i32 s4, 0x1bff
	s_nop 0
	v_pk_mul_f32 v[56:57], v[54:55], v[54:55]
	v_pk_mul_f32 v[58:59], v[52:53], v[52:53]
	s_nop 0
	v_mul_f32_e32 v0, v16, v16
	v_pk_mov_b32 v[60:61], v[58:59], v[56:57] op_sel:[1,0]
	v_mov_b32_e32 v59, v57
	v_pk_add_f32 v[56:57], v[60:61], v[58:59]
	v_pk_mul_f32 v[58:59], v[26:27], v[26:27]
	v_pk_mul_f32 v[60:61], v[24:25], v[24:25]
	v_mul_f32_e32 v2, v17, v17
	v_pk_mov_b32 v[62:63], v[60:61], v[58:59] op_sel:[1,0]
	v_mov_b32_e32 v61, v59
	v_pk_add_f32 v[58:59], v[62:63], v[60:61]
	v_pk_add_f32 v[56:57], v[56:57], v[56:57] op_sel:[0,1] op_sel_hi:[1,0]
	v_pk_add_f32 v[58:59], v[58:59], v[58:59] op_sel:[0,1] op_sel_hi:[1,0]
	v_mov_b32_e32 v57, v0
	v_mov_b32_e32 v59, v2
	v_mul_f32_e32 v0, v21, v21
	v_pk_add_f32 v[56:57], v[56:57], v[58:59]
	v_pk_fma_f32 v[58:59], v[20:21], v[20:21], v[0:1] op_sel_hi:[1,1,0]
	v_mul_f32_e32 v0, v23, v23
	v_mul_f32_e32 v4, v18, v18
	v_mul_f32_e32 v6, v19, v19
	v_pk_fma_f32 v[60:61], v[22:23], v[22:23], v[0:1] op_sel_hi:[1,1,0]
	v_mov_b32_e32 v59, v4
	v_mov_b32_e32 v61, v6
	v_pk_add_f32 v[58:59], v[58:59], v[60:61]
	s_nop 0
	v_pk_add_f32 v[56:57], v[56:57], v[58:59]
	s_nop 0
	v_add_f32_e32 v0, v56, v57
	v_lshl_add_u64 v[56:57], v[28:29], 0, v[48:49]
	v_lshl_add_u64 v[60:61], v[56:57], 0, s[6:7]
	v_add_co_u32_e32 v56, vcc, s76, v56
	v_add_f32_dpp v0, v0, v0 quad_perm:[1,0,3,2] row_mask:0xf bank_mask:0xf bound_ctrl:1
	s_nop 0
	v_addc_co_u32_e32 v57, vcc, 0, v57, vcc
	v_mov_b32_e32 v56, v132
	v_mov_b32_e32 v57, v133
	v_mov_b32_e32 v58, v134
	v_mov_b32_e32 v59, v135
	s_nop 0
	v_mov_b32_e32 v60, v136
	v_mov_b32_e32 v61, v137
	v_mov_b32_e32 v62, v138
	v_mov_b32_e32 v63, v139
	v_add_f32_dpp v0, v0, v0 quad_perm:[2,3,0,1] row_mask:0xf bank_mask:0xf bound_ctrl:1
	v_lshl_add_u64 v[48:49], v[48:49], 0, s[60:61]
	s_nop 0
	v_lshlrev_b32_e32 v64, 16, v56
	v_add_f32_dpp v0, v0, v0 row_half_mirror row_mask:0xf bank_mask:0xf bound_ctrl:1
	v_fmamk_f32 v0, v0, 0x3c000000, v194
	v_rsq_f32_e32 v6, v0
	v_mul_f32_e32 v0, 0xbfb8aa3b, v64
	v_exp_f32_e32 v0, v0
	v_mul_f32_e32 v65, v52, v6
	v_and_b32_e32 v52, 0xffff0000, v56
	v_add_f32_e32 v0, 1.0, v0
	v_rcp_f32_e32 v36, v0
	v_mul_f32_e32 v0, 0xbfb8aa3b, v52
	v_exp_f32_e32 v0, v0
	v_mul_f32_e32 v53, v53, v6
	v_mul_f32_e32 v21, v21, v6
	v_mul_f32_e32 v23, v23, v6
	v_add_f32_e32 v0, 1.0, v0
	v_rcp_f32_e32 v8, v0
	v_mul_f32_e32 v27, v27, v6
	v_mul_f32_e32 v19, v19, v6
	v_pk_mul_f32 v[64:65], v[36:37], v[64:65]
	v_pk_mul_f32 v[52:53], v[8:9], v[52:53]
	v_mul_f32_e32 v36, v64, v65
	v_mul_f32_e32 v8, v52, v53
	v_lshlrev_b32_e32 v52, 16, v57
	v_mul_f32_e32 v0, 0xbfb8aa3b, v52
	v_exp_f32_e32 v0, v0
	v_mul_f32_e32 v53, v54, v6
	v_add_f32_e32 v0, 1.0, v0
	v_rcp_f32_e32 v34, v0
	s_nop 0
	v_pk_mul_f32 v[52:53], v[34:35], v[52:53]
	s_nop 0
	v_mul_f32_e32 v34, v52, v53
	v_and_b32_e32 v52, 0xffff0000, v57
	v_mul_f32_e32 v0, 0xbfb8aa3b, v52
	v_exp_f32_e32 v0, v0
	v_mul_f32_e32 v53, v55, v6
	v_add_f32_e32 v0, 1.0, v0
	v_rcp_f32_e32 v10, v0
	s_nop 0
	v_pk_mul_f32 v[52:53], v[10:11], v[52:53]
	s_nop 0
	v_mul_f32_e32 v10, v52, v53
	v_lshlrev_b32_e32 v52, 16, v58
; __device__ __forceinline__ float bflo(unsigned w) { return __uint_as_float(w << 16); }
; __device__ __forceinline__ float bfhi(unsigned w) { return __uint_as_float(w & 0xffff0000u); }
; __device__ __forceinline__ float rsq_f(float x) { return __builtin_amdgcn_rsqf(x); }
; __device__ __forceinline__ void onorm_pass(const float* obuf, const bf16_t* z, const float* ong, bf16_t* ycat, int gw, int NGW, int lane) {
;     ...
;     for (int row = gw; row < MP; row += NGW) {
;         const float* op = obuf + (size_t)row * 1024 + lane * 16; const bf16_t* zp = z + (size_t)row * NZ + 7168 + lane * 16;
;         f32x4 v[4]; float ss = 0.f;
; #pragma unroll
;         for (int i = 0; i < 4; ++i) { v[i] = *(const f32x4*)(op + 4 * i); ss += (v[i].x * v[i].x + v[i].y * v[i].y) + (v[i].z * v[i].z + v[i].w * v[i].w); }
;         const u32x4 g0 = *(const u32x4*)zp, g1 = *(const u32x4*)(zp + 8);
;         ss += __builtin_bit_cast(float, __builtin_amdgcn_update_dpp(0, __builtin_bit_cast(int, ss), 0xB1, 0xF, 0xF, true));
;         ss += __builtin_bit_cast(float, __builtin_amdgcn_update_dpp(0, __builtin_bit_cast(int, ss), 0x4E, 0xF, 0xF, true));
;         ss += __builtin_bit_cast(float, __builtin_amdgcn_update_dpp(0, __builtin_bit_cast(int, ss), 0x141, 0xF, 0xF, true));
;         const float rstd = rsq_f(ss * (1.f / HD) + EPS);
;         float y[16];
;         y[0] = v[0].x * rstd * g[0].x * silu_f(bflo(g0.x)); y[1] = v[0].y * rstd * g[0].y * silu_f(bfhi(g0.x)); y[2] = v[0].z * rstd * g[0].z * silu_f(bflo(g0.y)); y[3] = v[0].w * rstd * g[0].w * silu_f(bfhi(g0.y));
;         y[4] = v[1].x * rstd * g[1].x * silu_f(bflo(g0.z)); y[5] = v[1].y * rstd * g[1].y * silu_f(bfhi(g0.z)); y[6] = v[1].z * rstd * g[1].z * silu_f(bflo(g0.w)); y[7] = v[1].w * rstd * g[1].w * silu_f(bfhi(g0.w));
;         y[8] = v[2].x * rstd * g[2].x * silu_f(bflo(g1.x)); y[9] = v[2].y * rstd * g[2].y * silu_f(bfhi(g1.x)); y[10] = v[2].z * rstd * g[2].z * silu_f(bflo(g1.y)); y[11] = v[2].w * rstd * g[2].w * silu_f(bfhi(g1.y));
;         y[12] = v[3].x * rstd * g[3].x * silu_f(bflo(g1.z)); y[13] = v[3].y * rstd * g[3].y * silu_f(bfhi(g1.z)); y[14] = v[3].z * rstd * g[3].z * silu_f(bflo(g1.w)); y[15] = v[3].w * rstd * g[3].w * silu_f(bfhi(g1.w));
;         bf16_t* yp = ycat + (size_t)row * DM + 1024 + lane * 16;
;         *(u32x4*)yp = pack8(y); *(u32x4*)(yp + 8) = pack8(y + 8);
	v_mul_f32_e32 v0, 0xbfb8aa3b, v52
	v_exp_f32_e32 v0, v0
	v_mul_f32_e32 v53, v24, v6
	v_add_f32_e32 v0, 1.0, v0
	v_rcp_f32_e32 v32, v0
	s_nop 0
	v_pk_mul_f32 v[52:53], v[32:33], v[52:53]
	s_nop 0
	v_mul_f32_e32 v24, v52, v53
	v_and_b32_e32 v52, 0xffff0000, v58
	v_mul_f32_e32 v0, 0xbfb8aa3b, v52
	v_exp_f32_e32 v0, v0
	v_mul_f32_e32 v53, v25, v6
	v_add_f32_e32 v0, 1.0, v0
	v_rcp_f32_e32 v12, v0
	s_nop 0
	v_pk_mul_f32 v[52:53], v[12:13], v[52:53]
	s_nop 0
	v_mul_f32_e32 v12, v52, v53
	v_lshlrev_b32_e32 v52, 16, v59
	v_mul_f32_e32 v0, 0xbfb8aa3b, v52
	v_exp_f32_e32 v0, v0
	v_mul_f32_e32 v53, v26, v6
	v_and_b32_e32 v26, 0xffff0000, v59
	v_cvt_pk_bf16_f32 v24, v24, v12
	v_add_f32_e32 v0, 1.0, v0
	v_rcp_f32_e32 v30, v0
	v_mul_f32_e32 v0, 0xbfb8aa3b, v26
	v_exp_f32_e32 v0, v0
	v_pk_mul_f32 v[52:53], v[30:31], v[52:53]
	s_nop 0
	v_mul_f32_e32 v25, v52, v53
	v_add_f32_e32 v0, 1.0, v0
	s_nop 0
	v_lshlrev_b32_e32 v52, 16, v60
	v_rcp_f32_e32 v14, v0
	v_mul_f32_e32 v0, 0xbfb8aa3b, v52
	v_exp_f32_e32 v0, v0
	v_mul_f32_e32 v53, v20, v6
	v_and_b32_e32 v20, 0xffff0000, v60
	v_pk_mul_f32 v[26:27], v[14:15], v[26:27]
	v_add_f32_e32 v0, 1.0, v0
	v_rcp_f32_e32 v44, v0
	v_mul_f32_e32 v0, 0xbfb8aa3b, v20
	v_exp_f32_e32 v0, v0
	v_mul_f32_e32 v26, v26, v27
	v_cvt_pk_bf16_f32 v25, v25, v26
	v_pk_mul_f32 v[52:53], v[44:45], v[52:53]
	v_add_f32_e32 v0, 1.0, v0
	v_rcp_f32_e32 v0, v0
	v_mul_f32_e32 v14, v52, v53
	v_pk_mul_f32 v[20:21], v[0:1], v[20:21]
	s_nop 0
	v_mul_f32_e32 v0, v20, v21
	v_lshlrev_b32_e32 v20, 16, v61
	v_mul_f32_e32 v2, 0xbfb8aa3b, v20
	v_exp_f32_e32 v2, v2
	v_mul_f32_e32 v21, v22, v6
	v_and_b32_e32 v22, 0xffff0000, v61
	v_add_f32_e32 v2, 1.0, v2
	v_rcp_f32_e32 v42, v2
	v_mul_f32_e32 v2, 0xbfb8aa3b, v22
	v_exp_f32_e32 v2, v2
	v_pk_mul_f32 v[20:21], v[42:43], v[20:21]
	s_nop 0
	v_mul_f32_e32 v20, v20, v21
	v_add_f32_e32 v2, 1.0, v2
	v_rcp_f32_e32 v2, v2
	s_nop 0
	v_pk_mul_f32 v[22:23], v[2:3], v[22:23]
	s_nop 0
	v_mul_f32_e32 v2, v22, v23
	v_lshlrev_b32_e32 v22, 16, v62
	v_mul_f32_e32 v4, 0xbfb8aa3b, v22
	v_exp_f32_e32 v4, v4
	v_mul_f32_e32 v23, v16, v6
	v_add_f32_e32 v4, 1.0, v4
	v_rcp_f32_e32 v40, v4
	s_nop 0
	v_pk_mul_f32 v[22:23], v[40:41], v[22:23]
	s_nop 0
	v_mul_f32_e32 v16, v22, v23
	v_and_b32_e32 v22, 0xffff0000, v62
	v_mul_f32_e32 v4, 0xbfb8aa3b, v22
	v_exp_f32_e32 v4, v4
	v_mul_f32_e32 v23, v17, v6
	v_add_f32_e32 v4, 1.0, v4
	v_rcp_f32_e32 v4, v4
	s_nop 0
	v_pk_mul_f32 v[22:23], v[4:5], v[22:23]
	s_nop 0
	v_mul_f32_e32 v4, v22, v23
	v_mul_f32_e32 v23, v18, v6
	v_and_b32_e32 v18, 0xffff0000, v63
	v_mul_f32_e32 v6, 0xbfb8aa3b, v18
	v_exp_f32_e32 v6, v6
	v_lshlrev_b32_e32 v22, 16, v63
	v_mul_f32_e32 v17, 0xbfb8aa3b, v22
	v_exp_f32_e32 v17, v17
	v_add_f32_e32 v6, 1.0, v6
	v_rcp_f32_e32 v6, v6
	v_add_f32_e32 v17, 1.0, v17
	v_rcp_f32_e32 v38, v17
	v_pk_mul_f32 v[18:19], v[6:7], v[18:19]
	v_pk_mul_f32 v[22:23], v[38:39], v[22:23]
	v_mul_f32_e32 v6, v18, v19
	v_lshl_add_u64 v[18:19], v[28:29], 0, v[46:47]
	v_add_co_u32_e32 v26, vcc, s5, v18
	v_lshl_add_u64 v[46:47], v[46:47], 0, s[84:85]
	s_nop 0
	v_addc_co_u32_e32 v27, vcc, 0, v19, vcc
	v_mul_f32_e32 v17, v22, v23
	v_cvt_pk_bf16_f32 v22, v36, v8
	v_cvt_pk_bf16_f32 v23, v34, v10
	global_store_dwordx4 v[26:27], v[22:25], off offset:2048
	v_cvt_pk_bf16_f32 v18, v14, v0
	v_cvt_pk_bf16_f32 v19, v20, v2
	v_cvt_pk_bf16_f32 v20, v16, v4
	v_cvt_pk_bf16_f32 v21, v17, v6
	global_store_dwordx4 v[26:27], v[18:21], off offset:2064
	global_load_dwordx4 v[116:119], v[200:201], off
	global_load_dwordx4 v[120:123], v[200:201], off offset:16
	global_load_dwordx4 v[124:127], v[200:201], off offset:32
	global_load_dwordx4 v[128:131], v[200:201], off offset:48
	global_load_dwordx4 v[132:135], v[202:203], off
	global_load_dwordx4 v[136:139], v[202:203], off offset:16
	v_lshl_add_u64 v[200:201], v[200:201], 0, s[84:85]
	v_lshl_add_u64 v[202:203], v[202:203], 0, s[60:61]
	v_lshl_add_u64 v[16:17], v[28:29], 0, v[50:51]
	v_lshl_add_u64 v[18:19], v[16:17], 0, s[8:9]
	v_add_co_u32_e32 v16, vcc, 0x28e00000, v16
	s_mov_b64 s[6:7], 0x13c03800
	s_nop 0
	v_addc_co_u32_e32 v17, vcc, 0, v17, vcc
	s_waitcnt vmcnt(24)
	v_mov_b32_e32 v52, v140
	v_mov_b32_e32 v53, v141
	v_mov_b32_e32 v54, v142
	v_mov_b32_e32 v55, v143
	v_mov_b32_e32 v20, v148
	v_mov_b32_e32 v21, v149
	v_mov_b32_e32 v22, v150
	v_mov_b32_e32 v23, v151
	v_mov_b32_e32 v24, v144
	v_mov_b32_e32 v25, v145
	v_mov_b32_e32 v26, v146
	v_mov_b32_e32 v27, v147
	s_nop 0
	v_mov_b32_e32 v16, v156
	v_mov_b32_e32 v17, v157
	v_mov_b32_e32 v18, v158
	v_mov_b32_e32 v19, v159
	s_mov_b32 s5, 0x20300000
	s_addk_i32 s4, 0x400
	v_lshl_add_u64 v[50:51], v[50:51], 0, s[84:85]
	s_cmpk_gt_i32 s4, 0x1bff
	s_nop 0
	v_pk_mul_f32 v[56:57], v[54:55], v[54:55]
	v_pk_mul_f32 v[58:59], v[52:53], v[52:53]
	s_nop 0
	v_mul_f32_e32 v0, v16, v16
	v_pk_mov_b32 v[60:61], v[58:59], v[56:57] op_sel:[1,0]
	v_mov_b32_e32 v59, v57
	v_pk_add_f32 v[56:57], v[60:61], v[58:59]
	v_pk_mul_f32 v[58:59], v[26:27], v[26:27]
	v_pk_mul_f32 v[60:61], v[24:25], v[24:25]
	v_mul_f32_e32 v2, v17, v17
	v_pk_mov_b32 v[62:63], v[60:61], v[58:59] op_sel:[1,0]
	v_mov_b32_e32 v61, v59
	v_pk_add_f32 v[58:59], v[62:63], v[60:61]
	v_pk_add_f32 v[56:57], v[56:57], v[56:57] op_sel:[0,1] op_sel_hi:[1,0]
	v_pk_add_f32 v[58:59], v[58:59], v[58:59] op_sel:[0,1] op_sel_hi:[1,0]
	v_mov_b32_e32 v57, v0
	v_mov_b32_e32 v59, v2
	v_mul_f32_e32 v0, v21, v21
	v_pk_add_f32 v[56:57], v[56:57], v[58:59]
	v_pk_fma_f32 v[58:59], v[20:21], v[20:21], v[0:1] op_sel_hi:[1,1,0]
	v_mul_f32_e32 v0, v23, v23
	v_mul_f32_e32 v4, v18, v18
	v_mul_f32_e32 v6, v19, v19
	v_pk_fma_f32 v[60:61], v[22:23], v[22:23], v[0:1] op_sel_hi:[1,1,0]
	v_mov_b32_e32 v59, v4
	v_mov_b32_e32 v61, v6
; __device__ __forceinline__ float bflo(unsigned w) { return __uint_as_float(w << 16); }
; __device__ __forceinline__ float bfhi(unsigned w) { return __uint_as_float(w & 0xffff0000u); }
; __device__ __forceinline__ float rsq_f(float x) { return __builtin_amdgcn_rsqf(x); }
; __device__ __forceinline__ void onorm_pass(const float* obuf, const bf16_t* z, const float* ong, bf16_t* ycat, int gw, int NGW, int lane) {
;     ...
;     for (int row = gw; row < MP; row += NGW) {
;         const float* op = obuf + (size_t)row * 1024 + lane * 16; const bf16_t* zp = z + (size_t)row * NZ + 7168 + lane * 16;
;         f32x4 v[4]; float ss = 0.f;
; #pragma unroll
;         for (int i = 0; i < 4; ++i) { v[i] = *(const f32x4*)(op + 4 * i); ss += (v[i].x * v[i].x + v[i].y * v[i].y) + (v[i].z * v[i].z + v[i].w * v[i].w); }
;         const u32x4 g0 = *(const u32x4*)zp, g1 = *(const u32x4*)(zp + 8);
;         ss += __builtin_bit_cast(float, __builtin_amdgcn_update_dpp(0, __builtin_bit_cast(int, ss), 0xB1, 0xF, 0xF, true));
;         ss += __builtin_bit_cast(float, __builtin_amdgcn_update_dpp(0, __builtin_bit_cast(int, ss), 0x4E, 0xF, 0xF, true));
;         ss += __builtin_bit_cast(float, __builtin_amdgcn_update_dpp(0, __builtin_bit_cast(int, ss), 0x141, 0xF, 0xF, true));
;         const float rstd = rsq_f(ss * (1.f / HD) + EPS);
;         float y[16];
;         y[0] = v[0].x * rstd * g[0].x * silu_f(bflo(g0.x)); y[1] = v[0].y * rstd * g[0].y * silu_f(bfhi(g0.x)); y[2] = v[0].z * rstd * g[0].z * silu_f(bflo(g0.y)); y[3] = v[0].w * rstd * g[0].w * silu_f(bfhi(g0.y));
;         y[4] = v[1].x * rstd * g[1].x * silu_f(bflo(g0.z)); y[5] = v[1].y * rstd * g[1].y * silu_f(bfhi(g0.z)); y[6] = v[1].z * rstd * g[1].z * silu_f(bflo(g0.w)); y[7] = v[1].w * rstd * g[1].w * silu_f(bfhi(g0.w));
;         y[8] = v[2].x * rstd * g[2].x * silu_f(bflo(g1.x)); y[9] = v[2].y * rstd * g[2].y * silu_f(bfhi(g1.x)); y[10] = v[2].z * rstd * g[2].z * silu_f(bflo(g1.y)); y[11] = v[2].w * rstd * g[2].w * silu_f(bfhi(g1.y));
;         y[12] = v[3].x * rstd * g[3].x * silu_f(bflo(g1.z)); y[13] = v[3].y * rstd * g[3].y * silu_f(bfhi(g1.z)); y[14] = v[3].z * rstd * g[3].z * silu_f(bflo(g1.w)); y[15] = v[3].w * rstd * g[3].w * silu_f(bfhi(g1.w));
;         bf16_t* yp = ycat + (size_t)row * DM + 1024 + lane * 16;
;         *(u32x4*)yp = pack8(y); *(u32x4*)(yp + 8) = pack8(y + 8);
	v_pk_add_f32 v[58:59], v[58:59], v[60:61]
	s_nop 0
	v_pk_add_f32 v[56:57], v[56:57], v[58:59]
	s_nop 0
	v_add_f32_e32 v0, v56, v57
	v_lshl_add_u64 v[56:57], v[28:29], 0, v[48:49]
	v_lshl_add_u64 v[60:61], v[56:57], 0, s[6:7]
	v_add_co_u32_e32 v56, vcc, s76, v56
	v_add_f32_dpp v0, v0, v0 quad_perm:[1,0,3,2] row_mask:0xf bank_mask:0xf bound_ctrl:1
	s_nop 0
	v_addc_co_u32_e32 v57, vcc, 0, v57, vcc
	v_mov_b32_e32 v56, v160
	v_mov_b32_e32 v57, v161
	v_mov_b32_e32 v58, v162
	v_mov_b32_e32 v59, v163
	s_nop 0
	v_mov_b32_e32 v60, v164
	v_mov_b32_e32 v61, v165
	v_mov_b32_e32 v62, v166
	v_mov_b32_e32 v63, v167
	v_add_f32_dpp v0, v0, v0 quad_perm:[2,3,0,1] row_mask:0xf bank_mask:0xf bound_ctrl:1
	v_lshl_add_u64 v[48:49], v[48:49], 0, s[60:61]
	s_nop 0
	v_lshlrev_b32_e32 v64, 16, v56
	v_add_f32_dpp v0, v0, v0 row_half_mirror row_mask:0xf bank_mask:0xf bound_ctrl:1
	v_fmamk_f32 v0, v0, 0x3c000000, v194
	v_rsq_f32_e32 v6, v0
	v_mul_f32_e32 v0, 0xbfb8aa3b, v64
	v_exp_f32_e32 v0, v0
	v_mul_f32_e32 v65, v52, v6
	v_and_b32_e32 v52, 0xffff0000, v56
	v_add_f32_e32 v0, 1.0, v0
	v_rcp_f32_e32 v36, v0
	v_mul_f32_e32 v0, 0xbfb8aa3b, v52
	v_exp_f32_e32 v0, v0
	v_mul_f32_e32 v53, v53, v6
	v_mul_f32_e32 v21, v21, v6
	v_mul_f32_e32 v23, v23, v6
	v_add_f32_e32 v0, 1.0, v0
	v_rcp_f32_e32 v8, v0
	v_mul_f32_e32 v27, v27, v6
	v_mul_f32_e32 v19, v19, v6
	v_pk_mul_f32 v[64:65], v[36:37], v[64:65]
	v_pk_mul_f32 v[52:53], v[8:9], v[52:53]
	v_mul_f32_e32 v36, v64, v65
	v_mul_f32_e32 v8, v52, v53
	v_lshlrev_b32_e32 v52, 16, v57
	v_mul_f32_e32 v0, 0xbfb8aa3b, v52
	v_exp_f32_e32 v0, v0
	v_mul_f32_e32 v53, v54, v6
	v_add_f32_e32 v0, 1.0, v0
	v_rcp_f32_e32 v34, v0
	s_nop 0
	v_pk_mul_f32 v[52:53], v[34:35], v[52:53]
	s_nop 0
	v_mul_f32_e32 v34, v52, v53
	v_and_b32_e32 v52, 0xffff0000, v57
	v_mul_f32_e32 v0, 0xbfb8aa3b, v52
	v_exp_f32_e32 v0, v0
	v_mul_f32_e32 v53, v55, v6
	v_add_f32_e32 v0, 1.0, v0
	v_rcp_f32_e32 v10, v0
	s_nop 0
	v_pk_mul_f32 v[52:53], v[10:11], v[52:53]
	s_nop 0
	v_mul_f32_e32 v10, v52, v53
	v_lshlrev_b32_e32 v52, 16, v58
	v_mul_f32_e32 v0, 0xbfb8aa3b, v52
	v_exp_f32_e32 v0, v0
	v_mul_f32_e32 v53, v24, v6
	v_add_f32_e32 v0, 1.0, v0
	v_rcp_f32_e32 v32, v0
	s_nop 0
	v_pk_mul_f32 v[52:53], v[32:33], v[52:53]
	s_nop 0
	v_mul_f32_e32 v24, v52, v53
	v_and_b32_e32 v52, 0xffff0000, v58
	v_mul_f32_e32 v0, 0xbfb8aa3b, v52
	v_exp_f32_e32 v0, v0
	v_mul_f32_e32 v53, v25, v6
	v_add_f32_e32 v0, 1.0, v0
	v_rcp_f32_e32 v12, v0
	s_nop 0
	v_pk_mul_f32 v[52:53], v[12:13], v[52:53]
	s_nop 0
	v_mul_f32_e32 v12, v52, v53
	v_lshlrev_b32_e32 v52, 16, v59
	v_mul_f32_e32 v0, 0xbfb8aa3b, v52
	v_exp_f32_e32 v0, v0
	v_mul_f32_e32 v53, v26, v6
	v_and_b32_e32 v26, 0xffff0000, v59
	v_cvt_pk_bf16_f32 v24, v24, v12
	v_add_f32_e32 v0, 1.0, v0
	v_rcp_f32_e32 v30, v0
	v_mul_f32_e32 v0, 0xbfb8aa3b, v26
	v_exp_f32_e32 v0, v0
	v_pk_mul_f32 v[52:53], v[30:31], v[52:53]
	s_nop 0
	v_mul_f32_e32 v25, v52, v53
	v_add_f32_e32 v0, 1.0, v0
	s_nop 0
	v_lshlrev_b32_e32 v52, 16, v60
	v_rcp_f32_e32 v14, v0
	v_mul_f32_e32 v0, 0xbfb8aa3b, v52
	v_exp_f32_e32 v0, v0
	v_mul_f32_e32 v53, v20, v6
	v_and_b32_e32 v20, 0xffff0000, v60
	v_pk_mul_f32 v[26:27], v[14:15], v[26:27]
	v_add_f32_e32 v0, 1.0, v0
	v_rcp_f32_e32 v44, v0
	v_mul_f32_e32 v0, 0xbfb8aa3b, v20
	v_exp_f32_e32 v0, v0
	v_mul_f32_e32 v26, v26, v27
	v_cvt_pk_bf16_f32 v25, v25, v26
	v_pk_mul_f32 v[52:53], v[44:45], v[52:53]
	v_add_f32_e32 v0, 1.0, v0
	v_rcp_f32_e32 v0, v0
	v_mul_f32_e32 v14, v52, v53
	v_pk_mul_f32 v[20:21], v[0:1], v[20:21]
	s_nop 0
	v_mul_f32_e32 v0, v20, v21
	v_lshlrev_b32_e32 v20, 16, v61
	v_mul_f32_e32 v2, 0xbfb8aa3b, v20
	v_exp_f32_e32 v2, v2
	v_mul_f32_e32 v21, v22, v6
	v_and_b32_e32 v22, 0xffff0000, v61
	v_add_f32_e32 v2, 1.0, v2
	v_rcp_f32_e32 v42, v2
	v_mul_f32_e32 v2, 0xbfb8aa3b, v22
	v_exp_f32_e32 v2, v2
	v_pk_mul_f32 v[20:21], v[42:43], v[20:21]
	s_nop 0
	v_mul_f32_e32 v20, v20, v21
	v_add_f32_e32 v2, 1.0, v2
	v_rcp_f32_e32 v2, v2
	s_nop 0
	v_pk_mul_f32 v[22:23], v[2:3], v[22:23]
	s_nop 0
	v_mul_f32_e32 v2, v22, v23
	v_lshlrev_b32_e32 v22, 16, v62
	v_mul_f32_e32 v4, 0xbfb8aa3b, v22
	v_exp_f32_e32 v4, v4
	v_mul_f32_e32 v23, v16, v6
	v_add_f32_e32 v4, 1.0, v4
	v_rcp_f32_e32 v40, v4
	s_nop 0
	v_pk_mul_f32 v[22:23], v[40:41], v[22:23]
	s_nop 0
	v_mul_f32_e32 v16, v22, v23
	v_and_b32_e32 v22, 0xffff0000, v62
	v_mul_f32_e32 v4, 0xbfb8aa3b, v22
	v_exp_f32_e32 v4, v4
	v_mul_f32_e32 v23, v17, v6
	v_add_f32_e32 v4, 1.0, v4
	v_rcp_f32_e32 v4, v4
	s_nop 0
	v_pk_mul_f32 v[22:23], v[4:5], v[22:23]
	s_nop 0
	v_mul_f32_e32 v4, v22, v23
	v_mul_f32_e32 v23, v18, v6
	v_and_b32_e32 v18, 0xffff0000, v63
	v_mul_f32_e32 v6, 0xbfb8aa3b, v18
	v_exp_f32_e32 v6, v6
	v_lshlrev_b32_e32 v22, 16, v63
	v_mul_f32_e32 v17, 0xbfb8aa3b, v22
	v_exp_f32_e32 v17, v17
	v_add_f32_e32 v6, 1.0, v6
	v_rcp_f32_e32 v6, v6
	v_add_f32_e32 v17, 1.0, v17
	v_rcp_f32_e32 v38, v17
	v_pk_mul_f32 v[18:19], v[6:7], v[18:19]
	v_pk_mul_f32 v[22:23], v[38:39], v[22:23]
	v_mul_f32_e32 v6, v18, v19
	v_lshl_add_u64 v[18:19], v[28:29], 0, v[46:47]
	v_add_co_u32_e32 v26, vcc, s5, v18
	v_lshl_add_u64 v[46:47], v[46:47], 0, s[84:85]
	s_nop 0
	v_addc_co_u32_e32 v27, vcc, 0, v19, vcc
	v_mul_f32_e32 v17, v22, v23
	v_cvt_pk_bf16_f32 v22, v36, v8
	v_cvt_pk_bf16_f32 v23, v34, v10
	global_store_dwordx4 v[26:27], v[22:25], off offset:2048
	v_cvt_pk_bf16_f32 v18, v14, v0
	v_cvt_pk_bf16_f32 v19, v20, v2
	v_cvt_pk_bf16_f32 v20, v16, v4
	v_cvt_pk_bf16_f32 v21, v17, v6
	global_store_dwordx4 v[26:27], v[18:21], off offset:2064
	global_load_dwordx4 v[140:143], v[200:201], off
	global_load_dwordx4 v[144:147], v[200:201], off offset:16
	global_load_dwordx4 v[148:151], v[200:201], off offset:32
	global_load_dwordx4 v[156:159], v[200:201], off offset:48
	global_load_dwordx4 v[160:163], v[202:203], off
	global_load_dwordx4 v[164:167], v[202:203], off offset:16
	v_lshl_add_u64 v[200:201], v[200:201], 0, s[84:85]
	v_lshl_add_u64 v[202:203], v[202:203], 0, s[60:61]
	v_lshl_add_u64 v[16:17], v[28:29], 0, v[50:51]
	v_lshl_add_u64 v[18:19], v[16:17], 0, s[8:9]
	v_add_co_u32_e32 v16, vcc, 0x28e00000, v16
	s_mov_b64 s[6:7], 0x13c03800
	s_nop 0
	v_addc_co_u32_e32 v17, vcc, 0, v17, vcc
	s_waitcnt vmcnt(24)
; __device__ __forceinline__ float bflo(unsigned w) { return __uint_as_float(w << 16); }
; __device__ __forceinline__ float bfhi(unsigned w) { return __uint_as_float(w & 0xffff0000u); }
; __device__ __forceinline__ float rsq_f(float x) { return __builtin_amdgcn_rsqf(x); }
; __device__ __forceinline__ void onorm_pass(const float* obuf, const bf16_t* z, const float* ong, bf16_t* ycat, int gw, int NGW, int lane) {
;     ...
;     for (int row = gw; row < MP; row += NGW) {
;         const float* op = obuf + (size_t)row * 1024 + lane * 16; const bf16_t* zp = z + (size_t)row * NZ + 7168 + lane * 16;
;         f32x4 v[4]; float ss = 0.f;
; #pragma unroll
;         for (int i = 0; i < 4; ++i) { v[i] = *(const f32x4*)(op + 4 * i); ss += (v[i].x * v[i].x + v[i].y * v[i].y) + (v[i].z * v[i].z + v[i].w * v[i].w); }
;         const u32x4 g0 = *(const u32x4*)zp, g1 = *(const u32x4*)(zp + 8);
;         ss += __builtin_bit_cast(float, __builtin_amdgcn_update_dpp(0, __builtin_bit_cast(int, ss), 0xB1, 0xF, 0xF, true));
;         ss += __builtin_bit_cast(float, __builtin_amdgcn_update_dpp(0, __builtin_bit_cast(int, ss), 0x4E, 0xF, 0xF, true));
;         ss += __builtin_bit_cast(float, __builtin_amdgcn_update_dpp(0, __builtin_bit_cast(int, ss), 0x141, 0xF, 0xF, true));
;         const float rstd = rsq_f(ss * (1.f / HD) + EPS);
;         float y[16];
;         y[0] = v[0].x * rstd * g[0].x * silu_f(bflo(g0.x)); y[1] = v[0].y * rstd * g[0].y * silu_f(bfhi(g0.x)); y[2] = v[0].z * rstd * g[0].z * silu_f(bflo(g0.y)); y[3] = v[0].w * rstd * g[0].w * silu_f(bfhi(g0.y));
;         y[4] = v[1].x * rstd * g[1].x * silu_f(bflo(g0.z)); y[5] = v[1].y * rstd * g[1].y * silu_f(bfhi(g0.z)); y[6] = v[1].z * rstd * g[1].z * silu_f(bflo(g0.w)); y[7] = v[1].w * rstd * g[1].w * silu_f(bfhi(g0.w));
;         y[8] = v[2].x * rstd * g[2].x * silu_f(bflo(g1.x)); y[9] = v[2].y * rstd * g[2].y * silu_f(bfhi(g1.x)); y[10] = v[2].z * rstd * g[2].z * silu_f(bflo(g1.y)); y[11] = v[2].w * rstd * g[2].w * silu_f(bfhi(g1.y));
;         y[12] = v[3].x * rstd * g[3].x * silu_f(bflo(g1.z)); y[13] = v[3].y * rstd * g[3].y * silu_f(bfhi(g1.z)); y[14] = v[3].z * rstd * g[3].z * silu_f(bflo(g1.w)); y[15] = v[3].w * rstd * g[3].w * silu_f(bfhi(g1.w));
;         bf16_t* yp = ycat + (size_t)row * DM + 1024 + lane * 16;
;         *(u32x4*)yp = pack8(y); *(u32x4*)(yp + 8) = pack8(y + 8);
	v_mov_b32_e32 v52, v68
	v_mov_b32_e32 v53, v69
	v_mov_b32_e32 v54, v70
	v_mov_b32_e32 v55, v71
	v_mov_b32_e32 v20, v76
	v_mov_b32_e32 v21, v77
	v_mov_b32_e32 v22, v78
	v_mov_b32_e32 v23, v79
	v_mov_b32_e32 v24, v72
	v_mov_b32_e32 v25, v73
	v_mov_b32_e32 v26, v74
	v_mov_b32_e32 v27, v75
	s_nop 0
	v_mov_b32_e32 v16, v80
	v_mov_b32_e32 v17, v81
	v_mov_b32_e32 v18, v82
	v_mov_b32_e32 v19, v83
	s_mov_b32 s5, 0x20300000
	s_addk_i32 s4, 0x400
	v_lshl_add_u64 v[50:51], v[50:51], 0, s[84:85]
	s_cmpk_gt_i32 s4, 0x1bff
	s_nop 0
	v_pk_mul_f32 v[56:57], v[54:55], v[54:55]
	v_pk_mul_f32 v[58:59], v[52:53], v[52:53]
	s_nop 0
	v_mul_f32_e32 v0, v16, v16
	v_pk_mov_b32 v[60:61], v[58:59], v[56:57] op_sel:[1,0]
	v_mov_b32_e32 v59, v57
	v_pk_add_f32 v[56:57], v[60:61], v[58:59]
	v_pk_mul_f32 v[58:59], v[26:27], v[26:27]
	v_pk_mul_f32 v[60:61], v[24:25], v[24:25]
	v_mul_f32_e32 v2, v17, v17
	v_pk_mov_b32 v[62:63], v[60:61], v[58:59] op_sel:[1,0]
	v_mov_b32_e32 v61, v59
	v_pk_add_f32 v[58:59], v[62:63], v[60:61]
	v_pk_add_f32 v[56:57], v[56:57], v[56:57] op_sel:[0,1] op_sel_hi:[1,0]
	v_pk_add_f32 v[58:59], v[58:59], v[58:59] op_sel:[0,1] op_sel_hi:[1,0]
	v_mov_b32_e32 v57, v0
	v_mov_b32_e32 v59, v2
	v_mul_f32_e32 v0, v21, v21
	v_pk_add_f32 v[56:57], v[56:57], v[58:59]
	v_pk_fma_f32 v[58:59], v[20:21], v[20:21], v[0:1] op_sel_hi:[1,1,0]
	v_mul_f32_e32 v0, v23, v23
	v_mul_f32_e32 v4, v18, v18
	v_mul_f32_e32 v6, v19, v19
	v_pk_fma_f32 v[60:61], v[22:23], v[22:23], v[0:1] op_sel_hi:[1,1,0]
	v_mov_b32_e32 v59, v4
	v_mov_b32_e32 v61, v6
	v_pk_add_f32 v[58:59], v[58:59], v[60:61]
	s_nop 0
	v_pk_add_f32 v[56:57], v[56:57], v[58:59]
	s_nop 0
	v_add_f32_e32 v0, v56, v57
	v_lshl_add_u64 v[56:57], v[28:29], 0, v[48:49]
	v_lshl_add_u64 v[60:61], v[56:57], 0, s[6:7]
	v_add_co_u32_e32 v56, vcc, s76, v56
	v_add_f32_dpp v0, v0, v0 quad_perm:[1,0,3,2] row_mask:0xf bank_mask:0xf bound_ctrl:1
	s_nop 0
	v_addc_co_u32_e32 v57, vcc, 0, v57, vcc
	v_mov_b32_e32 v56, v84
	v_mov_b32_e32 v57, v85
	v_mov_b32_e32 v58, v86
	v_mov_b32_e32 v59, v87
	s_nop 0
	v_mov_b32_e32 v60, v88
	v_mov_b32_e32 v61, v89
	v_mov_b32_e32 v62, v90
	v_mov_b32_e32 v63, v91
	v_add_f32_dpp v0, v0, v0 quad_perm:[2,3,0,1] row_mask:0xf bank_mask:0xf bound_ctrl:1
	v_lshl_add_u64 v[48:49], v[48:49], 0, s[60:61]
	s_nop 0
	v_lshlrev_b32_e32 v64, 16, v56
	v_add_f32_dpp v0, v0, v0 row_half_mirror row_mask:0xf bank_mask:0xf bound_ctrl:1
	v_fmamk_f32 v0, v0, 0x3c000000, v194
	v_rsq_f32_e32 v6, v0
	v_mul_f32_e32 v0, 0xbfb8aa3b, v64
	v_exp_f32_e32 v0, v0
	v_mul_f32_e32 v65, v52, v6
	v_and_b32_e32 v52, 0xffff0000, v56
	v_add_f32_e32 v0, 1.0, v0
	v_rcp_f32_e32 v36, v0
	v_mul_f32_e32 v0, 0xbfb8aa3b, v52
	v_exp_f32_e32 v0, v0
	v_mul_f32_e32 v53, v53, v6
	v_mul_f32_e32 v21, v21, v6
	v_mul_f32_e32 v23, v23, v6
	v_add_f32_e32 v0, 1.0, v0
	v_rcp_f32_e32 v8, v0
	v_mul_f32_e32 v27, v27, v6
	v_mul_f32_e32 v19, v19, v6
	v_pk_mul_f32 v[64:65], v[36:37], v[64:65]
	v_pk_mul_f32 v[52:53], v[8:9], v[52:53]
	v_mul_f32_e32 v36, v64, v65
	v_mul_f32_e32 v8, v52, v53
	v_lshlrev_b32_e32 v52, 16, v57
	v_mul_f32_e32 v0, 0xbfb8aa3b, v52
	v_exp_f32_e32 v0, v0
	v_mul_f32_e32 v53, v54, v6
	v_add_f32_e32 v0, 1.0, v0
	v_rcp_f32_e32 v34, v0
	s_nop 0
	v_pk_mul_f32 v[52:53], v[34:35], v[52:53]
	s_nop 0
	v_mul_f32_e32 v34, v52, v53
	v_and_b32_e32 v52, 0xffff0000, v57
	v_mul_f32_e32 v0, 0xbfb8aa3b, v52
	v_exp_f32_e32 v0, v0
	v_mul_f32_e32 v53, v55, v6
	v_add_f32_e32 v0, 1.0, v0
	v_rcp_f32_e32 v10, v0
	s_nop 0
	v_pk_mul_f32 v[52:53], v[10:11], v[52:53]
	s_nop 0
	v_mul_f32_e32 v10, v52, v53
	v_lshlrev_b32_e32 v52, 16, v58
	v_mul_f32_e32 v0, 0xbfb8aa3b, v52
	v_exp_f32_e32 v0, v0
	v_mul_f32_e32 v53, v24, v6
	v_add_f32_e32 v0, 1.0, v0
	v_rcp_f32_e32 v32, v0
	s_nop 0
	v_pk_mul_f32 v[52:53], v[32:33], v[52:53]
	s_nop 0
	v_mul_f32_e32 v24, v52, v53
	v_and_b32_e32 v52, 0xffff0000, v58
	v_mul_f32_e32 v0, 0xbfb8aa3b, v52
	v_exp_f32_e32 v0, v0
	v_mul_f32_e32 v53, v25, v6
	v_add_f32_e32 v0, 1.0, v0
	v_rcp_f32_e32 v12, v0
	s_nop 0
	v_pk_mul_f32 v[52:53], v[12:13], v[52:53]
	s_nop 0
	v_mul_f32_e32 v12, v52, v53
	v_lshlrev_b32_e32 v52, 16, v59
	v_mul_f32_e32 v0, 0xbfb8aa3b, v52
	v_exp_f32_e32 v0, v0
	v_mul_f32_e32 v53, v26, v6
	v_and_b32_e32 v26, 0xffff0000, v59
	v_cvt_pk_bf16_f32 v24, v24, v12
	v_add_f32_e32 v0, 1.0, v0
	v_rcp_f32_e32 v30, v0
	v_mul_f32_e32 v0, 0xbfb8aa3b, v26
	v_exp_f32_e32 v0, v0
	v_pk_mul_f32 v[52:53], v[30:31], v[52:53]
	s_nop 0
	v_mul_f32_e32 v25, v52, v53
	v_add_f32_e32 v0, 1.0, v0
	s_nop 0
	v_lshlrev_b32_e32 v52, 16, v60
	v_rcp_f32_e32 v14, v0
	v_mul_f32_e32 v0, 0xbfb8aa3b, v52
	v_exp_f32_e32 v0, v0
	v_mul_f32_e32 v53, v20, v6
	v_and_b32_e32 v20, 0xffff0000, v60
	v_pk_mul_f32 v[26:27], v[14:15], v[26:27]
	v_add_f32_e32 v0, 1.0, v0
	v_rcp_f32_e32 v44, v0
	v_mul_f32_e32 v0, 0xbfb8aa3b, v20
	v_exp_f32_e32 v0, v0
	v_mul_f32_e32 v26, v26, v27
	v_cvt_pk_bf16_f32 v25, v25, v26
	v_pk_mul_f32 v[52:53], v[44:45], v[52:53]
	v_add_f32_e32 v0, 1.0, v0
	v_rcp_f32_e32 v0, v0
	v_mul_f32_e32 v14, v52, v53
	v_pk_mul_f32 v[20:21], v[0:1], v[20:21]
	s_nop 0
	v_mul_f32_e32 v0, v20, v21
	v_lshlrev_b32_e32 v20, 16, v61
	v_mul_f32_e32 v2, 0xbfb8aa3b, v20
	v_exp_f32_e32 v2, v2
	v_mul_f32_e32 v21, v22, v6
	v_and_b32_e32 v22, 0xffff0000, v61
	v_add_f32_e32 v2, 1.0, v2
	v_rcp_f32_e32 v42, v2
	v_mul_f32_e32 v2, 0xbfb8aa3b, v22
	v_exp_f32_e32 v2, v2
	v_pk_mul_f32 v[20:21], v[42:43], v[20:21]
	s_nop 0
	v_mul_f32_e32 v20, v20, v21
	v_add_f32_e32 v2, 1.0, v2
	v_rcp_f32_e32 v2, v2
	s_nop 0
	v_pk_mul_f32 v[22:23], v[2:3], v[22:23]
	s_nop 0
	v_mul_f32_e32 v2, v22, v23
	v_lshlrev_b32_e32 v22, 16, v62
	v_mul_f32_e32 v4, 0xbfb8aa3b, v22
	v_exp_f32_e32 v4, v4
	v_mul_f32_e32 v23, v16, v6
; __device__ __forceinline__ float bflo(unsigned w) { return __uint_as_float(w << 16); }
; __device__ __forceinline__ float bfhi(unsigned w) { return __uint_as_float(w & 0xffff0000u); }
; __device__ __forceinline__ float rsq_f(float x) { return __builtin_amdgcn_rsqf(x); }
; __device__ __forceinline__ void onorm_pass(const float* obuf, const bf16_t* z, const float* ong, bf16_t* ycat, int gw, int NGW, int lane) {
;     ...
;     for (int row = gw; row < MP; row += NGW) {
;         const float* op = obuf + (size_t)row * 1024 + lane * 16; const bf16_t* zp = z + (size_t)row * NZ + 7168 + lane * 16;
;         f32x4 v[4]; float ss = 0.f;
; #pragma unroll
;         for (int i = 0; i < 4; ++i) { v[i] = *(const f32x4*)(op + 4 * i); ss += (v[i].x * v[i].x + v[i].y * v[i].y) + (v[i].z * v[i].z + v[i].w * v[i].w); }
;         const u32x4 g0 = *(const u32x4*)zp, g1 = *(const u32x4*)(zp + 8);
;         ss += __builtin_bit_cast(float, __builtin_amdgcn_update_dpp(0, __builtin_bit_cast(int, ss), 0xB1, 0xF, 0xF, true));
;         ss += __builtin_bit_cast(float, __builtin_amdgcn_update_dpp(0, __builtin_bit_cast(int, ss), 0x4E, 0xF, 0xF, true));
;         ss += __builtin_bit_cast(float, __builtin_amdgcn_update_dpp(0, __builtin_bit_cast(int, ss), 0x141, 0xF, 0xF, true));
;         const float rstd = rsq_f(ss * (1.f / HD) + EPS);
;         float y[16];
;         y[0] = v[0].x * rstd * g[0].x * silu_f(bflo(g0.x)); y[1] = v[0].y * rstd * g[0].y * silu_f(bfhi(g0.x)); y[2] = v[0].z * rstd * g[0].z * silu_f(bflo(g0.y)); y[3] = v[0].w * rstd * g[0].w * silu_f(bfhi(g0.y));
;         y[4] = v[1].x * rstd * g[1].x * silu_f(bflo(g0.z)); y[5] = v[1].y * rstd * g[1].y * silu_f(bfhi(g0.z)); y[6] = v[1].z * rstd * g[1].z * silu_f(bflo(g0.w)); y[7] = v[1].w * rstd * g[1].w * silu_f(bfhi(g0.w));
;         y[8] = v[2].x * rstd * g[2].x * silu_f(bflo(g1.x)); y[9] = v[2].y * rstd * g[2].y * silu_f(bfhi(g1.x)); y[10] = v[2].z * rstd * g[2].z * silu_f(bflo(g1.y)); y[11] = v[2].w * rstd * g[2].w * silu_f(bfhi(g1.y));
;         y[12] = v[3].x * rstd * g[3].x * silu_f(bflo(g1.z)); y[13] = v[3].y * rstd * g[3].y * silu_f(bfhi(g1.z)); y[14] = v[3].z * rstd * g[3].z * silu_f(bflo(g1.w)); y[15] = v[3].w * rstd * g[3].w * silu_f(bfhi(g1.w));
;         bf16_t* yp = ycat + (size_t)row * DM + 1024 + lane * 16;
;         *(u32x4*)yp = pack8(y); *(u32x4*)(yp + 8) = pack8(y + 8);
	v_add_f32_e32 v4, 1.0, v4
	v_rcp_f32_e32 v40, v4
	s_nop 0
	v_pk_mul_f32 v[22:23], v[40:41], v[22:23]
	s_nop 0
	v_mul_f32_e32 v16, v22, v23
	v_and_b32_e32 v22, 0xffff0000, v62
	v_mul_f32_e32 v4, 0xbfb8aa3b, v22
	v_exp_f32_e32 v4, v4
	v_mul_f32_e32 v23, v17, v6
	v_add_f32_e32 v4, 1.0, v4
	v_rcp_f32_e32 v4, v4
	s_nop 0
	v_pk_mul_f32 v[22:23], v[4:5], v[22:23]
	s_nop 0
	v_mul_f32_e32 v4, v22, v23
	v_mul_f32_e32 v23, v18, v6
	v_and_b32_e32 v18, 0xffff0000, v63
	v_mul_f32_e32 v6, 0xbfb8aa3b, v18
	v_exp_f32_e32 v6, v6
	v_lshlrev_b32_e32 v22, 16, v63
	v_mul_f32_e32 v17, 0xbfb8aa3b, v22
	v_exp_f32_e32 v17, v17
	v_add_f32_e32 v6, 1.0, v6
	v_rcp_f32_e32 v6, v6
	v_add_f32_e32 v17, 1.0, v17
	v_rcp_f32_e32 v38, v17
	v_pk_mul_f32 v[18:19], v[6:7], v[18:19]
	v_pk_mul_f32 v[22:23], v[38:39], v[22:23]
	v_mul_f32_e32 v6, v18, v19
	v_lshl_add_u64 v[18:19], v[28:29], 0, v[46:47]
	v_add_co_u32_e32 v26, vcc, s5, v18
	v_lshl_add_u64 v[46:47], v[46:47], 0, s[84:85]
	s_nop 0
	v_addc_co_u32_e32 v27, vcc, 0, v19, vcc
	v_mul_f32_e32 v17, v22, v23
	v_cvt_pk_bf16_f32 v22, v36, v8
	v_cvt_pk_bf16_f32 v23, v34, v10
	global_store_dwordx4 v[26:27], v[22:25], off offset:2048
	v_cvt_pk_bf16_f32 v18, v14, v0
	v_cvt_pk_bf16_f32 v19, v20, v2
	v_cvt_pk_bf16_f32 v20, v16, v4
	v_cvt_pk_bf16_f32 v21, v17, v6
	global_store_dwordx4 v[26:27], v[18:21], off offset:2064
	v_lshl_add_u64 v[16:17], v[28:29], 0, v[50:51]
	v_lshl_add_u64 v[18:19], v[16:17], 0, s[8:9]
	v_add_co_u32_e32 v16, vcc, 0x28e00000, v16
	s_mov_b64 s[6:7], 0x13c03800
	s_nop 0
	v_addc_co_u32_e32 v17, vcc, 0, v17, vcc
	s_waitcnt vmcnt(18)
	v_mov_b32_e32 v52, v92
	v_mov_b32_e32 v53, v93
	v_mov_b32_e32 v54, v94
	v_mov_b32_e32 v55, v95
	v_mov_b32_e32 v20, v100
	v_mov_b32_e32 v21, v101
	v_mov_b32_e32 v22, v102
	v_mov_b32_e32 v23, v103
	v_mov_b32_e32 v24, v96
	v_mov_b32_e32 v25, v97
	v_mov_b32_e32 v26, v98
	v_mov_b32_e32 v27, v99
	s_nop 0
	v_mov_b32_e32 v16, v104
	v_mov_b32_e32 v17, v105
	v_mov_b32_e32 v18, v106
	v_mov_b32_e32 v19, v107
	s_mov_b32 s5, 0x20300000
	s_addk_i32 s4, 0x400
	v_lshl_add_u64 v[50:51], v[50:51], 0, s[84:85]
	s_cmpk_gt_i32 s4, 0x1bff
	s_nop 0
	v_pk_mul_f32 v[56:57], v[54:55], v[54:55]
	v_pk_mul_f32 v[58:59], v[52:53], v[52:53]
	s_nop 0
	v_mul_f32_e32 v0, v16, v16
	v_pk_mov_b32 v[60:61], v[58:59], v[56:57] op_sel:[1,0]
	v_mov_b32_e32 v59, v57
	v_pk_add_f32 v[56:57], v[60:61], v[58:59]
	v_pk_mul_f32 v[58:59], v[26:27], v[26:27]
	v_pk_mul_f32 v[60:61], v[24:25], v[24:25]
	v_mul_f32_e32 v2, v17, v17
	v_pk_mov_b32 v[62:63], v[60:61], v[58:59] op_sel:[1,0]
	v_mov_b32_e32 v61, v59
	v_pk_add_f32 v[58:59], v[62:63], v[60:61]
	v_pk_add_f32 v[56:57], v[56:57], v[56:57] op_sel:[0,1] op_sel_hi:[1,0]
	v_pk_add_f32 v[58:59], v[58:59], v[58:59] op_sel:[0,1] op_sel_hi:[1,0]
	v_mov_b32_e32 v57, v0
	v_mov_b32_e32 v59, v2
	v_mul_f32_e32 v0, v21, v21
	v_pk_add_f32 v[56:57], v[56:57], v[58:59]
	v_pk_fma_f32 v[58:59], v[20:21], v[20:21], v[0:1] op_sel_hi:[1,1,0]
	v_mul_f32_e32 v0, v23, v23
	v_mul_f32_e32 v4, v18, v18
	v_mul_f32_e32 v6, v19, v19
	v_pk_fma_f32 v[60:61], v[22:23], v[22:23], v[0:1] op_sel_hi:[1,1,0]
	v_mov_b32_e32 v59, v4
	v_mov_b32_e32 v61, v6
	v_pk_add_f32 v[58:59], v[58:59], v[60:61]
	s_nop 0
	v_pk_add_f32 v[56:57], v[56:57], v[58:59]
	s_nop 0
	v_add_f32_e32 v0, v56, v57
	v_lshl_add_u64 v[56:57], v[28:29], 0, v[48:49]
	v_lshl_add_u64 v[60:61], v[56:57], 0, s[6:7]
	v_add_co_u32_e32 v56, vcc, s76, v56
	v_add_f32_dpp v0, v0, v0 quad_perm:[1,0,3,2] row_mask:0xf bank_mask:0xf bound_ctrl:1
	s_nop 0
	v_addc_co_u32_e32 v57, vcc, 0, v57, vcc
	v_mov_b32_e32 v56, v108
	v_mov_b32_e32 v57, v109
	v_mov_b32_e32 v58, v110
	v_mov_b32_e32 v59, v111
	s_nop 0
	v_mov_b32_e32 v60, v112
	v_mov_b32_e32 v61, v113
	v_mov_b32_e32 v62, v114
	v_mov_b32_e32 v63, v115
	v_add_f32_dpp v0, v0, v0 quad_perm:[2,3,0,1] row_mask:0xf bank_mask:0xf bound_ctrl:1
	v_lshl_add_u64 v[48:49], v[48:49], 0, s[60:61]
	s_nop 0
	v_lshlrev_b32_e32 v64, 16, v56
	v_add_f32_dpp v0, v0, v0 row_half_mirror row_mask:0xf bank_mask:0xf bound_ctrl:1
	v_fmamk_f32 v0, v0, 0x3c000000, v194
	v_rsq_f32_e32 v6, v0
	v_mul_f32_e32 v0, 0xbfb8aa3b, v64
	v_exp_f32_e32 v0, v0
	v_mul_f32_e32 v65, v52, v6
	v_and_b32_e32 v52, 0xffff0000, v56
	v_add_f32_e32 v0, 1.0, v0
	v_rcp_f32_e32 v36, v0
	v_mul_f32_e32 v0, 0xbfb8aa3b, v52
	v_exp_f32_e32 v0, v0
	v_mul_f32_e32 v53, v53, v6
	v_mul_f32_e32 v21, v21, v6
	v_mul_f32_e32 v23, v23, v6
	v_add_f32_e32 v0, 1.0, v0
	v_rcp_f32_e32 v8, v0
	v_mul_f32_e32 v27, v27, v6
	v_mul_f32_e32 v19, v19, v6
	v_pk_mul_f32 v[64:65], v[36:37], v[64:65]
	v_pk_mul_f32 v[52:53], v[8:9], v[52:53]
	v_mul_f32_e32 v36, v64, v65
	v_mul_f32_e32 v8, v52, v53
	v_lshlrev_b32_e32 v52, 16, v57
	v_mul_f32_e32 v0, 0xbfb8aa3b, v52
	v_exp_f32_e32 v0, v0
	v_mul_f32_e32 v53, v54, v6
	v_add_f32_e32 v0, 1.0, v0
	v_rcp_f32_e32 v34, v0
	s_nop 0
	v_pk_mul_f32 v[52:53], v[34:35], v[52:53]
	s_nop 0
	v_mul_f32_e32 v34, v52, v53
	v_and_b32_e32 v52, 0xffff0000, v57
	v_mul_f32_e32 v0, 0xbfb8aa3b, v52
	v_exp_f32_e32 v0, v0
	v_mul_f32_e32 v53, v55, v6
	v_add_f32_e32 v0, 1.0, v0
	v_rcp_f32_e32 v10, v0
	s_nop 0
	v_pk_mul_f32 v[52:53], v[10:11], v[52:53]
	s_nop 0
	v_mul_f32_e32 v10, v52, v53
	v_lshlrev_b32_e32 v52, 16, v58
	v_mul_f32_e32 v0, 0xbfb8aa3b, v52
	v_exp_f32_e32 v0, v0
	v_mul_f32_e32 v53, v24, v6
	v_add_f32_e32 v0, 1.0, v0
	v_rcp_f32_e32 v32, v0
	s_nop 0
	v_pk_mul_f32 v[52:53], v[32:33], v[52:53]
	s_nop 0
	v_mul_f32_e32 v24, v52, v53
	v_and_b32_e32 v52, 0xffff0000, v58
	v_mul_f32_e32 v0, 0xbfb8aa3b, v52
	v_exp_f32_e32 v0, v0
	v_mul_f32_e32 v53, v25, v6
	v_add_f32_e32 v0, 1.0, v0
	v_rcp_f32_e32 v12, v0
	s_nop 0
	v_pk_mul_f32 v[52:53], v[12:13], v[52:53]
	s_nop 0
	v_mul_f32_e32 v12, v52, v53
; __device__ __forceinline__ float bflo(unsigned w) { return __uint_as_float(w << 16); }
; __device__ __forceinline__ float bfhi(unsigned w) { return __uint_as_float(w & 0xffff0000u); }
; __device__ __forceinline__ float rsq_f(float x) { return __builtin_amdgcn_rsqf(x); }
; __device__ __forceinline__ void onorm_pass(const float* obuf, const bf16_t* z, const float* ong, bf16_t* ycat, int gw, int NGW, int lane) {
;     ...
;     for (int row = gw; row < MP; row += NGW) {
;         const float* op = obuf + (size_t)row * 1024 + lane * 16; const bf16_t* zp = z + (size_t)row * NZ + 7168 + lane * 16;
;         f32x4 v[4]; float ss = 0.f;
; #pragma unroll
;         for (int i = 0; i < 4; ++i) { v[i] = *(const f32x4*)(op + 4 * i); ss += (v[i].x * v[i].x + v[i].y * v[i].y) + (v[i].z * v[i].z + v[i].w * v[i].w); }
;         const u32x4 g0 = *(const u32x4*)zp, g1 = *(const u32x4*)(zp + 8);
;         ss += __builtin_bit_cast(float, __builtin_amdgcn_update_dpp(0, __builtin_bit_cast(int, ss), 0xB1, 0xF, 0xF, true));
;         ss += __builtin_bit_cast(float, __builtin_amdgcn_update_dpp(0, __builtin_bit_cast(int, ss), 0x4E, 0xF, 0xF, true));
;         ss += __builtin_bit_cast(float, __builtin_amdgcn_update_dpp(0, __builtin_bit_cast(int, ss), 0x141, 0xF, 0xF, true));
;         const float rstd = rsq_f(ss * (1.f / HD) + EPS);
;         float y[16];
;         y[0] = v[0].x * rstd * g[0].x * silu_f(bflo(g0.x)); y[1] = v[0].y * rstd * g[0].y * silu_f(bfhi(g0.x)); y[2] = v[0].z * rstd * g[0].z * silu_f(bflo(g0.y)); y[3] = v[0].w * rstd * g[0].w * silu_f(bfhi(g0.y));
;         y[4] = v[1].x * rstd * g[1].x * silu_f(bflo(g0.z)); y[5] = v[1].y * rstd * g[1].y * silu_f(bfhi(g0.z)); y[6] = v[1].z * rstd * g[1].z * silu_f(bflo(g0.w)); y[7] = v[1].w * rstd * g[1].w * silu_f(bfhi(g0.w));
;         y[8] = v[2].x * rstd * g[2].x * silu_f(bflo(g1.x)); y[9] = v[2].y * rstd * g[2].y * silu_f(bfhi(g1.x)); y[10] = v[2].z * rstd * g[2].z * silu_f(bflo(g1.y)); y[11] = v[2].w * rstd * g[2].w * silu_f(bfhi(g1.y));
;         y[12] = v[3].x * rstd * g[3].x * silu_f(bflo(g1.z)); y[13] = v[3].y * rstd * g[3].y * silu_f(bfhi(g1.z)); y[14] = v[3].z * rstd * g[3].z * silu_f(bflo(g1.w)); y[15] = v[3].w * rstd * g[3].w * silu_f(bfhi(g1.w));
;         bf16_t* yp = ycat + (size_t)row * DM + 1024 + lane * 16;
;         *(u32x4*)yp = pack8(y); *(u32x4*)(yp + 8) = pack8(y + 8);
	v_lshlrev_b32_e32 v52, 16, v59
	v_mul_f32_e32 v0, 0xbfb8aa3b, v52
	v_exp_f32_e32 v0, v0
	v_mul_f32_e32 v53, v26, v6
	v_and_b32_e32 v26, 0xffff0000, v59
	v_cvt_pk_bf16_f32 v24, v24, v12
	v_add_f32_e32 v0, 1.0, v0
	v_rcp_f32_e32 v30, v0
	v_mul_f32_e32 v0, 0xbfb8aa3b, v26
	v_exp_f32_e32 v0, v0
	v_pk_mul_f32 v[52:53], v[30:31], v[52:53]
	s_nop 0
	v_mul_f32_e32 v25, v52, v53
	v_add_f32_e32 v0, 1.0, v0
	s_nop 0
	v_lshlrev_b32_e32 v52, 16, v60
	v_rcp_f32_e32 v14, v0
	v_mul_f32_e32 v0, 0xbfb8aa3b, v52
	v_exp_f32_e32 v0, v0
	v_mul_f32_e32 v53, v20, v6
	v_and_b32_e32 v20, 0xffff0000, v60
	v_pk_mul_f32 v[26:27], v[14:15], v[26:27]
	v_add_f32_e32 v0, 1.0, v0
	v_rcp_f32_e32 v44, v0
	v_mul_f32_e32 v0, 0xbfb8aa3b, v20
	v_exp_f32_e32 v0, v0
	v_mul_f32_e32 v26, v26, v27
	v_cvt_pk_bf16_f32 v25, v25, v26
	v_pk_mul_f32 v[52:53], v[44:45], v[52:53]
	v_add_f32_e32 v0, 1.0, v0
	v_rcp_f32_e32 v0, v0
	v_mul_f32_e32 v14, v52, v53
	v_pk_mul_f32 v[20:21], v[0:1], v[20:21]
	s_nop 0
	v_mul_f32_e32 v0, v20, v21
	v_lshlrev_b32_e32 v20, 16, v61
	v_mul_f32_e32 v2, 0xbfb8aa3b, v20
	v_exp_f32_e32 v2, v2
	v_mul_f32_e32 v21, v22, v6
	v_and_b32_e32 v22, 0xffff0000, v61
	v_add_f32_e32 v2, 1.0, v2
	v_rcp_f32_e32 v42, v2
	v_mul_f32_e32 v2, 0xbfb8aa3b, v22
	v_exp_f32_e32 v2, v2
	v_pk_mul_f32 v[20:21], v[42:43], v[20:21]
	s_nop 0
	v_mul_f32_e32 v20, v20, v21
	v_add_f32_e32 v2, 1.0, v2
	v_rcp_f32_e32 v2, v2
	s_nop 0
	v_pk_mul_f32 v[22:23], v[2:3], v[22:23]
	s_nop 0
	v_mul_f32_e32 v2, v22, v23
	v_lshlrev_b32_e32 v22, 16, v62
	v_mul_f32_e32 v4, 0xbfb8aa3b, v22
	v_exp_f32_e32 v4, v4
	v_mul_f32_e32 v23, v16, v6
	v_add_f32_e32 v4, 1.0, v4
	v_rcp_f32_e32 v40, v4
	s_nop 0
	v_pk_mul_f32 v[22:23], v[40:41], v[22:23]
	s_nop 0
	v_mul_f32_e32 v16, v22, v23
	v_and_b32_e32 v22, 0xffff0000, v62
	v_mul_f32_e32 v4, 0xbfb8aa3b, v22
	v_exp_f32_e32 v4, v4
	v_mul_f32_e32 v23, v17, v6
	v_add_f32_e32 v4, 1.0, v4
	v_rcp_f32_e32 v4, v4
	s_nop 0
	v_pk_mul_f32 v[22:23], v[4:5], v[22:23]
	s_nop 0
	v_mul_f32_e32 v4, v22, v23
	v_mul_f32_e32 v23, v18, v6
	v_and_b32_e32 v18, 0xffff0000, v63
	v_mul_f32_e32 v6, 0xbfb8aa3b, v18
	v_exp_f32_e32 v6, v6
	v_lshlrev_b32_e32 v22, 16, v63
	v_mul_f32_e32 v17, 0xbfb8aa3b, v22
	v_exp_f32_e32 v17, v17
	v_add_f32_e32 v6, 1.0, v6
	v_rcp_f32_e32 v6, v6
	v_add_f32_e32 v17, 1.0, v17
	v_rcp_f32_e32 v38, v17
	v_pk_mul_f32 v[18:19], v[6:7], v[18:19]
	v_pk_mul_f32 v[22:23], v[38:39], v[22:23]
	v_mul_f32_e32 v6, v18, v19
	v_lshl_add_u64 v[18:19], v[28:29], 0, v[46:47]
	v_add_co_u32_e32 v26, vcc, s5, v18
	v_lshl_add_u64 v[46:47], v[46:47], 0, s[84:85]
	s_nop 0
	v_addc_co_u32_e32 v27, vcc, 0, v19, vcc
	v_mul_f32_e32 v17, v22, v23
	v_cvt_pk_bf16_f32 v22, v36, v8
	v_cvt_pk_bf16_f32 v23, v34, v10
	global_store_dwordx4 v[26:27], v[22:25], off offset:2048
	v_cvt_pk_bf16_f32 v18, v14, v0
	v_cvt_pk_bf16_f32 v19, v20, v2
	v_cvt_pk_bf16_f32 v20, v16, v4
	v_cvt_pk_bf16_f32 v21, v17, v6
	global_store_dwordx4 v[26:27], v[18:21], off offset:2064
	v_lshl_add_u64 v[16:17], v[28:29], 0, v[50:51]
	v_lshl_add_u64 v[18:19], v[16:17], 0, s[8:9]
	v_add_co_u32_e32 v16, vcc, 0x28e00000, v16
	s_mov_b64 s[6:7], 0x13c03800
	s_nop 0
	v_addc_co_u32_e32 v17, vcc, 0, v17, vcc
	s_waitcnt vmcnt(12)
	v_mov_b32_e32 v52, v116
	v_mov_b32_e32 v53, v117
	v_mov_b32_e32 v54, v118
	v_mov_b32_e32 v55, v119
	v_mov_b32_e32 v20, v124
	v_mov_b32_e32 v21, v125
	v_mov_b32_e32 v22, v126
	v_mov_b32_e32 v23, v127
	v_mov_b32_e32 v24, v120
	v_mov_b32_e32 v25, v121
	v_mov_b32_e32 v26, v122
	v_mov_b32_e32 v27, v123
	s_nop 0
	v_mov_b32_e32 v16, v128
	v_mov_b32_e32 v17, v129
	v_mov_b32_e32 v18, v130
	v_mov_b32_e32 v19, v131
	s_mov_b32 s5, 0x20300000
	s_addk_i32 s4, 0x400
	v_lshl_add_u64 v[50:51], v[50:51], 0, s[84:85]
	s_cmpk_gt_i32 s4, 0x1bff
	s_nop 0
	v_pk_mul_f32 v[56:57], v[54:55], v[54:55]
	v_pk_mul_f32 v[58:59], v[52:53], v[52:53]
	s_nop 0
	v_mul_f32_e32 v0, v16, v16
	v_pk_mov_b32 v[60:61], v[58:59], v[56:57] op_sel:[1,0]
	v_mov_b32_e32 v59, v57
	v_pk_add_f32 v[56:57], v[60:61], v[58:59]
	v_pk_mul_f32 v[58:59], v[26:27], v[26:27]
	v_pk_mul_f32 v[60:61], v[24:25], v[24:25]
	v_mul_f32_e32 v2, v17, v17
	v_pk_mov_b32 v[62:63], v[60:61], v[58:59] op_sel:[1,0]
	v_mov_b32_e32 v61, v59
	v_pk_add_f32 v[58:59], v[62:63], v[60:61]
	v_pk_add_f32 v[56:57], v[56:57], v[56:57] op_sel:[0,1] op_sel_hi:[1,0]
	v_pk_add_f32 v[58:59], v[58:59], v[58:59] op_sel:[0,1] op_sel_hi:[1,0]
	v_mov_b32_e32 v57, v0
	v_mov_b32_e32 v59, v2
	v_mul_f32_e32 v0, v21, v21
	v_pk_add_f32 v[56:57], v[56:57], v[58:59]
	v_pk_fma_f32 v[58:59], v[20:21], v[20:21], v[0:1] op_sel_hi:[1,1,0]
	v_mul_f32_e32 v0, v23, v23
	v_mul_f32_e32 v4, v18, v18
	v_mul_f32_e32 v6, v19, v19
	v_pk_fma_f32 v[60:61], v[22:23], v[22:23], v[0:1] op_sel_hi:[1,1,0]
	v_mov_b32_e32 v59, v4
	v_mov_b32_e32 v61, v6
	v_pk_add_f32 v[58:59], v[58:59], v[60:61]
	s_nop 0
	v_pk_add_f32 v[56:57], v[56:57], v[58:59]
	s_nop 0
	v_add_f32_e32 v0, v56, v57
	v_lshl_add_u64 v[56:57], v[28:29], 0, v[48:49]
	v_lshl_add_u64 v[60:61], v[56:57], 0, s[6:7]
	v_add_co_u32_e32 v56, vcc, s76, v56
	v_add_f32_dpp v0, v0, v0 quad_perm:[1,0,3,2] row_mask:0xf bank_mask:0xf bound_ctrl:1
	s_nop 0
	v_addc_co_u32_e32 v57, vcc, 0, v57, vcc
	v_mov_b32_e32 v56, v132
	v_mov_b32_e32 v57, v133
	v_mov_b32_e32 v58, v134
	v_mov_b32_e32 v59, v135
	s_nop 0
	v_mov_b32_e32 v60, v136
	v_mov_b32_e32 v61, v137
	v_mov_b32_e32 v62, v138
	v_mov_b32_e32 v63, v139
	v_add_f32_dpp v0, v0, v0 quad_perm:[2,3,0,1] row_mask:0xf bank_mask:0xf bound_ctrl:1
	v_lshl_add_u64 v[48:49], v[48:49], 0, s[60:61]
	s_nop 0
	v_lshlrev_b32_e32 v64, 16, v56
	v_add_f32_dpp v0, v0, v0 row_half_mirror row_mask:0xf bank_mask:0xf bound_ctrl:1
	v_fmamk_f32 v0, v0, 0x3c000000, v194
; __device__ __forceinline__ float bflo(unsigned w) { return __uint_as_float(w << 16); }
; __device__ __forceinline__ float bfhi(unsigned w) { return __uint_as_float(w & 0xffff0000u); }
; __device__ __forceinline__ float rsq_f(float x) { return __builtin_amdgcn_rsqf(x); }
; __device__ __forceinline__ void onorm_pass(const float* obuf, const bf16_t* z, const float* ong, bf16_t* ycat, int gw, int NGW, int lane) {
;     ...
;     for (int row = gw; row < MP; row += NGW) {
;         const float* op = obuf + (size_t)row * 1024 + lane * 16; const bf16_t* zp = z + (size_t)row * NZ + 7168 + lane * 16;
;         f32x4 v[4]; float ss = 0.f;
; #pragma unroll
;         for (int i = 0; i < 4; ++i) { v[i] = *(const f32x4*)(op + 4 * i); ss += (v[i].x * v[i].x + v[i].y * v[i].y) + (v[i].z * v[i].z + v[i].w * v[i].w); }
;         const u32x4 g0 = *(const u32x4*)zp, g1 = *(const u32x4*)(zp + 8);
;         ss += __builtin_bit_cast(float, __builtin_amdgcn_update_dpp(0, __builtin_bit_cast(int, ss), 0xB1, 0xF, 0xF, true));
;         ss += __builtin_bit_cast(float, __builtin_amdgcn_update_dpp(0, __builtin_bit_cast(int, ss), 0x4E, 0xF, 0xF, true));
;         ss += __builtin_bit_cast(float, __builtin_amdgcn_update_dpp(0, __builtin_bit_cast(int, ss), 0x141, 0xF, 0xF, true));
;         const float rstd = rsq_f(ss * (1.f / HD) + EPS);
;         float y[16];
;         y[0] = v[0].x * rstd * g[0].x * silu_f(bflo(g0.x)); y[1] = v[0].y * rstd * g[0].y * silu_f(bfhi(g0.x)); y[2] = v[0].z * rstd * g[0].z * silu_f(bflo(g0.y)); y[3] = v[0].w * rstd * g[0].w * silu_f(bfhi(g0.y));
;         y[4] = v[1].x * rstd * g[1].x * silu_f(bflo(g0.z)); y[5] = v[1].y * rstd * g[1].y * silu_f(bfhi(g0.z)); y[6] = v[1].z * rstd * g[1].z * silu_f(bflo(g0.w)); y[7] = v[1].w * rstd * g[1].w * silu_f(bfhi(g0.w));
;         y[8] = v[2].x * rstd * g[2].x * silu_f(bflo(g1.x)); y[9] = v[2].y * rstd * g[2].y * silu_f(bfhi(g1.x)); y[10] = v[2].z * rstd * g[2].z * silu_f(bflo(g1.y)); y[11] = v[2].w * rstd * g[2].w * silu_f(bfhi(g1.y));
;         y[12] = v[3].x * rstd * g[3].x * silu_f(bflo(g1.z)); y[13] = v[3].y * rstd * g[3].y * silu_f(bfhi(g1.z)); y[14] = v[3].z * rstd * g[3].z * silu_f(bflo(g1.w)); y[15] = v[3].w * rstd * g[3].w * silu_f(bfhi(g1.w));
;         bf16_t* yp = ycat + (size_t)row * DM + 1024 + lane * 16;
;         *(u32x4*)yp = pack8(y); *(u32x4*)(yp + 8) = pack8(y + 8);
	v_rsq_f32_e32 v6, v0
	v_mul_f32_e32 v0, 0xbfb8aa3b, v64
	v_exp_f32_e32 v0, v0
	v_mul_f32_e32 v65, v52, v6
	v_and_b32_e32 v52, 0xffff0000, v56
	v_add_f32_e32 v0, 1.0, v0
	v_rcp_f32_e32 v36, v0
	v_mul_f32_e32 v0, 0xbfb8aa3b, v52
	v_exp_f32_e32 v0, v0
	v_mul_f32_e32 v53, v53, v6
	v_mul_f32_e32 v21, v21, v6
	v_mul_f32_e32 v23, v23, v6
	v_add_f32_e32 v0, 1.0, v0
	v_rcp_f32_e32 v8, v0
	v_mul_f32_e32 v27, v27, v6
	v_mul_f32_e32 v19, v19, v6
	v_pk_mul_f32 v[64:65], v[36:37], v[64:65]
	v_pk_mul_f32 v[52:53], v[8:9], v[52:53]
	v_mul_f32_e32 v36, v64, v65
	v_mul_f32_e32 v8, v52, v53
	v_lshlrev_b32_e32 v52, 16, v57
	v_mul_f32_e32 v0, 0xbfb8aa3b, v52
	v_exp_f32_e32 v0, v0
	v_mul_f32_e32 v53, v54, v6
	v_add_f32_e32 v0, 1.0, v0
	v_rcp_f32_e32 v34, v0
	s_nop 0
	v_pk_mul_f32 v[52:53], v[34:35], v[52:53]
	s_nop 0
	v_mul_f32_e32 v34, v52, v53
	v_and_b32_e32 v52, 0xffff0000, v57
	v_mul_f32_e32 v0, 0xbfb8aa3b, v52
	v_exp_f32_e32 v0, v0
	v_mul_f32_e32 v53, v55, v6
	v_add_f32_e32 v0, 1.0, v0
	v_rcp_f32_e32 v10, v0
	s_nop 0
	v_pk_mul_f32 v[52:53], v[10:11], v[52:53]
	s_nop 0
	v_mul_f32_e32 v10, v52, v53
	v_lshlrev_b32_e32 v52, 16, v58
	v_mul_f32_e32 v0, 0xbfb8aa3b, v52
	v_exp_f32_e32 v0, v0
	v_mul_f32_e32 v53, v24, v6
	v_add_f32_e32 v0, 1.0, v0
	v_rcp_f32_e32 v32, v0
	s_nop 0
	v_pk_mul_f32 v[52:53], v[32:33], v[52:53]
	s_nop 0
	v_mul_f32_e32 v24, v52, v53
	v_and_b32_e32 v52, 0xffff0000, v58
	v_mul_f32_e32 v0, 0xbfb8aa3b, v52
	v_exp_f32_e32 v0, v0
	v_mul_f32_e32 v53, v25, v6
	v_add_f32_e32 v0, 1.0, v0
	v_rcp_f32_e32 v12, v0
	s_nop 0
	v_pk_mul_f32 v[52:53], v[12:13], v[52:53]
	s_nop 0
	v_mul_f32_e32 v12, v52, v53
	v_lshlrev_b32_e32 v52, 16, v59
	v_mul_f32_e32 v0, 0xbfb8aa3b, v52
	v_exp_f32_e32 v0, v0
	v_mul_f32_e32 v53, v26, v6
	v_and_b32_e32 v26, 0xffff0000, v59
	v_cvt_pk_bf16_f32 v24, v24, v12
	v_add_f32_e32 v0, 1.0, v0
	v_rcp_f32_e32 v30, v0
	v_mul_f32_e32 v0, 0xbfb8aa3b, v26
	v_exp_f32_e32 v0, v0
	v_pk_mul_f32 v[52:53], v[30:31], v[52:53]
	s_nop 0
	v_mul_f32_e32 v25, v52, v53
	v_add_f32_e32 v0, 1.0, v0
	s_nop 0
	v_lshlrev_b32_e32 v52, 16, v60
	v_rcp_f32_e32 v14, v0
	v_mul_f32_e32 v0, 0xbfb8aa3b, v52
	v_exp_f32_e32 v0, v0
	v_mul_f32_e32 v53, v20, v6
	v_and_b32_e32 v20, 0xffff0000, v60
	v_pk_mul_f32 v[26:27], v[14:15], v[26:27]
	v_add_f32_e32 v0, 1.0, v0
	v_rcp_f32_e32 v44, v0
	v_mul_f32_e32 v0, 0xbfb8aa3b, v20
	v_exp_f32_e32 v0, v0
	v_mul_f32_e32 v26, v26, v27
	v_cvt_pk_bf16_f32 v25, v25, v26
	v_pk_mul_f32 v[52:53], v[44:45], v[52:53]
	v_add_f32_e32 v0, 1.0, v0
	v_rcp_f32_e32 v0, v0
	v_mul_f32_e32 v14, v52, v53
	v_pk_mul_f32 v[20:21], v[0:1], v[20:21]
	s_nop 0
	v_mul_f32_e32 v0, v20, v21
	v_lshlrev_b32_e32 v20, 16, v61
	v_mul_f32_e32 v2, 0xbfb8aa3b, v20
	v_exp_f32_e32 v2, v2
	v_mul_f32_e32 v21, v22, v6
	v_and_b32_e32 v22, 0xffff0000, v61
	v_add_f32_e32 v2, 1.0, v2
	v_rcp_f32_e32 v42, v2
	v_mul_f32_e32 v2, 0xbfb8aa3b, v22
	v_exp_f32_e32 v2, v2
	v_pk_mul_f32 v[20:21], v[42:43], v[20:21]
	s_nop 0
	v_mul_f32_e32 v20, v20, v21
	v_add_f32_e32 v2, 1.0, v2
	v_rcp_f32_e32 v2, v2
	s_nop 0
	v_pk_mul_f32 v[22:23], v[2:3], v[22:23]
	s_nop 0
	v_mul_f32_e32 v2, v22, v23
	v_lshlrev_b32_e32 v22, 16, v62
	v_mul_f32_e32 v4, 0xbfb8aa3b, v22
	v_exp_f32_e32 v4, v4
	v_mul_f32_e32 v23, v16, v6
	v_add_f32_e32 v4, 1.0, v4
	v_rcp_f32_e32 v40, v4
	s_nop 0
	v_pk_mul_f32 v[22:23], v[40:41], v[22:23]
	s_nop 0
	v_mul_f32_e32 v16, v22, v23
	v_and_b32_e32 v22, 0xffff0000, v62
	v_mul_f32_e32 v4, 0xbfb8aa3b, v22
	v_exp_f32_e32 v4, v4
	v_mul_f32_e32 v23, v17, v6
	v_add_f32_e32 v4, 1.0, v4
	v_rcp_f32_e32 v4, v4
	s_nop 0
	v_pk_mul_f32 v[22:23], v[4:5], v[22:23]
	s_nop 0
	v_mul_f32_e32 v4, v22, v23
	v_mul_f32_e32 v23, v18, v6
	v_and_b32_e32 v18, 0xffff0000, v63
	v_mul_f32_e32 v6, 0xbfb8aa3b, v18
	v_exp_f32_e32 v6, v6
	v_lshlrev_b32_e32 v22, 16, v63
	v_mul_f32_e32 v17, 0xbfb8aa3b, v22
	v_exp_f32_e32 v17, v17
	v_add_f32_e32 v6, 1.0, v6
	v_rcp_f32_e32 v6, v6
	v_add_f32_e32 v17, 1.0, v17
	v_rcp_f32_e32 v38, v17
	v_pk_mul_f32 v[18:19], v[6:7], v[18:19]
	v_pk_mul_f32 v[22:23], v[38:39], v[22:23]
	v_mul_f32_e32 v6, v18, v19
	v_lshl_add_u64 v[18:19], v[28:29], 0, v[46:47]
	v_add_co_u32_e32 v26, vcc, s5, v18
	v_lshl_add_u64 v[46:47], v[46:47], 0, s[84:85]
	s_nop 0
	v_addc_co_u32_e32 v27, vcc, 0, v19, vcc
	v_mul_f32_e32 v17, v22, v23
	v_cvt_pk_bf16_f32 v22, v36, v8
	v_cvt_pk_bf16_f32 v23, v34, v10
	global_store_dwordx4 v[26:27], v[22:25], off offset:2048
	v_cvt_pk_bf16_f32 v18, v14, v0
	v_cvt_pk_bf16_f32 v19, v20, v2
	v_cvt_pk_bf16_f32 v20, v16, v4
	v_cvt_pk_bf16_f32 v21, v17, v6
	global_store_dwordx4 v[26:27], v[18:21], off offset:2064
	v_lshl_add_u64 v[16:17], v[28:29], 0, v[50:51]
	v_lshl_add_u64 v[18:19], v[16:17], 0, s[8:9]
	v_add_co_u32_e32 v16, vcc, 0x28e00000, v16
	s_mov_b64 s[6:7], 0x13c03800
	s_nop 0
	v_addc_co_u32_e32 v17, vcc, 0, v17, vcc
	s_waitcnt vmcnt(6)
; __device__ __forceinline__ float bflo(unsigned w) { return __uint_as_float(w << 16); }
; __device__ __forceinline__ float bfhi(unsigned w) { return __uint_as_float(w & 0xffff0000u); }
; __device__ __forceinline__ float rsq_f(float x) { return __builtin_amdgcn_rsqf(x); }
; __device__ __forceinline__ void onorm_pass(const float* obuf, const bf16_t* z, const float* ong, bf16_t* ycat, int gw, int NGW, int lane) {
;     ...
;     for (int row = gw; row < MP; row += NGW) {
;         const float* op = obuf + (size_t)row * 1024 + lane * 16; const bf16_t* zp = z + (size_t)row * NZ + 7168 + lane * 16;
;         f32x4 v[4]; float ss = 0.f;
; #pragma unroll
;         for (int i = 0; i < 4; ++i) { v[i] = *(const f32x4*)(op + 4 * i); ss += (v[i].x * v[i].x + v[i].y * v[i].y) + (v[i].z * v[i].z + v[i].w * v[i].w); }
;         const u32x4 g0 = *(const u32x4*)zp, g1 = *(const u32x4*)(zp + 8);
;         ss += __builtin_bit_cast(float, __builtin_amdgcn_update_dpp(0, __builtin_bit_cast(int, ss), 0xB1, 0xF, 0xF, true));
;         ss += __builtin_bit_cast(float, __builtin_amdgcn_update_dpp(0, __builtin_bit_cast(int, ss), 0x4E, 0xF, 0xF, true));
;         ss += __builtin_bit_cast(float, __builtin_amdgcn_update_dpp(0, __builtin_bit_cast(int, ss), 0x141, 0xF, 0xF, true));
;         const float rstd = rsq_f(ss * (1.f / HD) + EPS);
;         float y[16];
;         y[0] = v[0].x * rstd * g[0].x * silu_f(bflo(g0.x)); y[1] = v[0].y * rstd * g[0].y * silu_f(bfhi(g0.x)); y[2] = v[0].z * rstd * g[0].z * silu_f(bflo(g0.y)); y[3] = v[0].w * rstd * g[0].w * silu_f(bfhi(g0.y));
;         y[4] = v[1].x * rstd * g[1].x * silu_f(bflo(g0.z)); y[5] = v[1].y * rstd * g[1].y * silu_f(bfhi(g0.z)); y[6] = v[1].z * rstd * g[1].z * silu_f(bflo(g0.w)); y[7] = v[1].w * rstd * g[1].w * silu_f(bfhi(g0.w));
;         y[8] = v[2].x * rstd * g[2].x * silu_f(bflo(g1.x)); y[9] = v[2].y * rstd * g[2].y * silu_f(bfhi(g1.x)); y[10] = v[2].z * rstd * g[2].z * silu_f(bflo(g1.y)); y[11] = v[2].w * rstd * g[2].w * silu_f(bfhi(g1.y));
;         y[12] = v[3].x * rstd * g[3].x * silu_f(bflo(g1.z)); y[13] = v[3].y * rstd * g[3].y * silu_f(bfhi(g1.z)); y[14] = v[3].z * rstd * g[3].z * silu_f(bflo(g1.w)); y[15] = v[3].w * rstd * g[3].w * silu_f(bfhi(g1.w));
;         bf16_t* yp = ycat + (size_t)row * DM + 1024 + lane * 16;
;         *(u32x4*)yp = pack8(y); *(u32x4*)(yp + 8) = pack8(y + 8);
	v_mov_b32_e32 v52, v140
	v_mov_b32_e32 v53, v141
	v_mov_b32_e32 v54, v142
	v_mov_b32_e32 v55, v143
	v_mov_b32_e32 v20, v148
	v_mov_b32_e32 v21, v149
	v_mov_b32_e32 v22, v150
	v_mov_b32_e32 v23, v151
	v_mov_b32_e32 v24, v144
	v_mov_b32_e32 v25, v145
	v_mov_b32_e32 v26, v146
	v_mov_b32_e32 v27, v147
	s_nop 0
	v_mov_b32_e32 v16, v156
	v_mov_b32_e32 v17, v157
	v_mov_b32_e32 v18, v158
	v_mov_b32_e32 v19, v159
	s_mov_b32 s5, 0x20300000
	s_addk_i32 s4, 0x400
	v_lshl_add_u64 v[50:51], v[50:51], 0, s[84:85]
	s_cmpk_gt_i32 s4, 0x1bff
	s_nop 0
	v_pk_mul_f32 v[56:57], v[54:55], v[54:55]
	v_pk_mul_f32 v[58:59], v[52:53], v[52:53]
	s_nop 0
	v_mul_f32_e32 v0, v16, v16
	v_pk_mov_b32 v[60:61], v[58:59], v[56:57] op_sel:[1,0]
	v_mov_b32_e32 v59, v57
	v_pk_add_f32 v[56:57], v[60:61], v[58:59]
	v_pk_mul_f32 v[58:59], v[26:27], v[26:27]
	v_pk_mul_f32 v[60:61], v[24:25], v[24:25]
	v_mul_f32_e32 v2, v17, v17
	v_pk_mov_b32 v[62:63], v[60:61], v[58:59] op_sel:[1,0]
	v_mov_b32_e32 v61, v59
	v_pk_add_f32 v[58:59], v[62:63], v[60:61]
	v_pk_add_f32 v[56:57], v[56:57], v[56:57] op_sel:[0,1] op_sel_hi:[1,0]
	v_pk_add_f32 v[58:59], v[58:59], v[58:59] op_sel:[0,1] op_sel_hi:[1,0]
	v_mov_b32_e32 v57, v0
	v_mov_b32_e32 v59, v2
	v_mul_f32_e32 v0, v21, v21
	v_pk_add_f32 v[56:57], v[56:57], v[58:59]
	v_pk_fma_f32 v[58:59], v[20:21], v[20:21], v[0:1] op_sel_hi:[1,1,0]
	v_mul_f32_e32 v0, v23, v23
	v_mul_f32_e32 v4, v18, v18
	v_mul_f32_e32 v6, v19, v19
	v_pk_fma_f32 v[60:61], v[22:23], v[22:23], v[0:1] op_sel_hi:[1,1,0]
	v_mov_b32_e32 v59, v4
	v_mov_b32_e32 v61, v6
	v_pk_add_f32 v[58:59], v[58:59], v[60:61]
	s_nop 0
	v_pk_add_f32 v[56:57], v[56:57], v[58:59]
	s_nop 0
	v_add_f32_e32 v0, v56, v57
	v_lshl_add_u64 v[56:57], v[28:29], 0, v[48:49]
	v_lshl_add_u64 v[60:61], v[56:57], 0, s[6:7]
	v_add_co_u32_e32 v56, vcc, s76, v56
	v_add_f32_dpp v0, v0, v0 quad_perm:[1,0,3,2] row_mask:0xf bank_mask:0xf bound_ctrl:1
	s_nop 0
	v_addc_co_u32_e32 v57, vcc, 0, v57, vcc
	v_mov_b32_e32 v56, v160
	v_mov_b32_e32 v57, v161
	v_mov_b32_e32 v58, v162
	v_mov_b32_e32 v59, v163
	s_nop 0
	v_mov_b32_e32 v60, v164
	v_mov_b32_e32 v61, v165
	v_mov_b32_e32 v62, v166
	v_mov_b32_e32 v63, v167
	v_add_f32_dpp v0, v0, v0 quad_perm:[2,3,0,1] row_mask:0xf bank_mask:0xf bound_ctrl:1
	v_lshl_add_u64 v[48:49], v[48:49], 0, s[60:61]
	s_nop 0
	v_lshlrev_b32_e32 v64, 16, v56
	v_add_f32_dpp v0, v0, v0 row_half_mirror row_mask:0xf bank_mask:0xf bound_ctrl:1
	v_fmamk_f32 v0, v0, 0x3c000000, v194
	v_rsq_f32_e32 v6, v0
	v_mul_f32_e32 v0, 0xbfb8aa3b, v64
	v_exp_f32_e32 v0, v0
	v_mul_f32_e32 v65, v52, v6
	v_and_b32_e32 v52, 0xffff0000, v56
	v_add_f32_e32 v0, 1.0, v0
	v_rcp_f32_e32 v36, v0
	v_mul_f32_e32 v0, 0xbfb8aa3b, v52
	v_exp_f32_e32 v0, v0
	v_mul_f32_e32 v53, v53, v6
	v_mul_f32_e32 v21, v21, v6
	v_mul_f32_e32 v23, v23, v6
	v_add_f32_e32 v0, 1.0, v0
	v_rcp_f32_e32 v8, v0
	v_mul_f32_e32 v27, v27, v6
	v_mul_f32_e32 v19, v19, v6
	v_pk_mul_f32 v[64:65], v[36:37], v[64:65]
	v_pk_mul_f32 v[52:53], v[8:9], v[52:53]
	v_mul_f32_e32 v36, v64, v65
	v_mul_f32_e32 v8, v52, v53
	v_lshlrev_b32_e32 v52, 16, v57
	v_mul_f32_e32 v0, 0xbfb8aa3b, v52
	v_exp_f32_e32 v0, v0
	v_mul_f32_e32 v53, v54, v6
	v_add_f32_e32 v0, 1.0, v0
	v_rcp_f32_e32 v34, v0
	s_nop 0
	v_pk_mul_f32 v[52:53], v[34:35], v[52:53]
	s_nop 0
	v_mul_f32_e32 v34, v52, v53
	v_and_b32_e32 v52, 0xffff0000, v57
	v_mul_f32_e32 v0, 0xbfb8aa3b, v52
	v_exp_f32_e32 v0, v0
	v_mul_f32_e32 v53, v55, v6
	v_add_f32_e32 v0, 1.0, v0
	v_rcp_f32_e32 v10, v0
	s_nop 0
	v_pk_mul_f32 v[52:53], v[10:11], v[52:53]
	s_nop 0
	v_mul_f32_e32 v10, v52, v53
	v_lshlrev_b32_e32 v52, 16, v58
	v_mul_f32_e32 v0, 0xbfb8aa3b, v52
	v_exp_f32_e32 v0, v0
	v_mul_f32_e32 v53, v24, v6
	v_add_f32_e32 v0, 1.0, v0
	v_rcp_f32_e32 v32, v0
	s_nop 0
	v_pk_mul_f32 v[52:53], v[32:33], v[52:53]
	s_nop 0
	v_mul_f32_e32 v24, v52, v53
	v_and_b32_e32 v52, 0xffff0000, v58
	v_mul_f32_e32 v0, 0xbfb8aa3b, v52
	v_exp_f32_e32 v0, v0
	v_mul_f32_e32 v53, v25, v6
	v_add_f32_e32 v0, 1.0, v0
	v_rcp_f32_e32 v12, v0
	s_nop 0
	v_pk_mul_f32 v[52:53], v[12:13], v[52:53]
	s_nop 0
	v_mul_f32_e32 v12, v52, v53
	v_lshlrev_b32_e32 v52, 16, v59
	v_mul_f32_e32 v0, 0xbfb8aa3b, v52
	v_exp_f32_e32 v0, v0
	v_mul_f32_e32 v53, v26, v6
	v_and_b32_e32 v26, 0xffff0000, v59
	v_cvt_pk_bf16_f32 v24, v24, v12
	v_add_f32_e32 v0, 1.0, v0
	v_rcp_f32_e32 v30, v0
	v_mul_f32_e32 v0, 0xbfb8aa3b, v26
	v_exp_f32_e32 v0, v0
	v_pk_mul_f32 v[52:53], v[30:31], v[52:53]
	s_nop 0
	v_mul_f32_e32 v25, v52, v53
	v_add_f32_e32 v0, 1.0, v0
	s_nop 0
	v_lshlrev_b32_e32 v52, 16, v60
	v_rcp_f32_e32 v14, v0
	v_mul_f32_e32 v0, 0xbfb8aa3b, v52
	v_exp_f32_e32 v0, v0
	v_mul_f32_e32 v53, v20, v6
	v_and_b32_e32 v20, 0xffff0000, v60
	v_pk_mul_f32 v[26:27], v[14:15], v[26:27]
	v_add_f32_e32 v0, 1.0, v0
	v_rcp_f32_e32 v44, v0
	v_mul_f32_e32 v0, 0xbfb8aa3b, v20
	v_exp_f32_e32 v0, v0
	v_mul_f32_e32 v26, v26, v27
	v_cvt_pk_bf16_f32 v25, v25, v26
	v_pk_mul_f32 v[52:53], v[44:45], v[52:53]
	v_add_f32_e32 v0, 1.0, v0
	v_rcp_f32_e32 v0, v0
	v_mul_f32_e32 v14, v52, v53
	v_pk_mul_f32 v[20:21], v[0:1], v[20:21]
	s_nop 0
	v_mul_f32_e32 v0, v20, v21
	v_lshlrev_b32_e32 v20, 16, v61
	v_mul_f32_e32 v2, 0xbfb8aa3b, v20
	v_exp_f32_e32 v2, v2
	v_mul_f32_e32 v21, v22, v6
	v_and_b32_e32 v22, 0xffff0000, v61
	v_add_f32_e32 v2, 1.0, v2
	v_rcp_f32_e32 v42, v2
	v_mul_f32_e32 v2, 0xbfb8aa3b, v22
	v_exp_f32_e32 v2, v2
	v_pk_mul_f32 v[20:21], v[42:43], v[20:21]
	s_nop 0
	v_mul_f32_e32 v20, v20, v21
	v_add_f32_e32 v2, 1.0, v2
	v_rcp_f32_e32 v2, v2
	s_nop 0
	v_pk_mul_f32 v[22:23], v[2:3], v[22:23]
	s_nop 0
	v_mul_f32_e32 v2, v22, v23
	v_lshlrev_b32_e32 v22, 16, v62
	v_mul_f32_e32 v4, 0xbfb8aa3b, v22
	v_exp_f32_e32 v4, v4
	v_mul_f32_e32 v23, v16, v6
	v_add_f32_e32 v4, 1.0, v4
	v_rcp_f32_e32 v40, v4
	s_nop 0
	v_pk_mul_f32 v[22:23], v[40:41], v[22:23]
	s_nop 0
	v_mul_f32_e32 v16, v22, v23
	v_and_b32_e32 v22, 0xffff0000, v62
	v_mul_f32_e32 v4, 0xbfb8aa3b, v22
	v_exp_f32_e32 v4, v4
	v_mul_f32_e32 v23, v17, v6
	v_add_f32_e32 v4, 1.0, v4
	v_rcp_f32_e32 v4, v4
	s_nop 0
	v_pk_mul_f32 v[22:23], v[4:5], v[22:23]
	s_nop 0
	v_mul_f32_e32 v4, v22, v23
	v_mul_f32_e32 v23, v18, v6
	v_and_b32_e32 v18, 0xffff0000, v63
	v_mul_f32_e32 v6, 0xbfb8aa3b, v18
	v_exp_f32_e32 v6, v6
	v_lshlrev_b32_e32 v22, 16, v63
	v_mul_f32_e32 v17, 0xbfb8aa3b, v22
	v_exp_f32_e32 v17, v17
	v_add_f32_e32 v6, 1.0, v6
	v_rcp_f32_e32 v6, v6
	v_add_f32_e32 v17, 1.0, v17
	v_rcp_f32_e32 v38, v17
	v_pk_mul_f32 v[18:19], v[6:7], v[18:19]
	v_pk_mul_f32 v[22:23], v[38:39], v[22:23]
	v_mul_f32_e32 v6, v18, v19
	v_lshl_add_u64 v[18:19], v[28:29], 0, v[46:47]
	v_add_co_u32_e32 v26, vcc, s5, v18
	v_lshl_add_u64 v[46:47], v[46:47], 0, s[84:85]
	s_nop 0
	v_addc_co_u32_e32 v27, vcc, 0, v19, vcc
	v_mul_f32_e32 v17, v22, v23
	v_cvt_pk_bf16_f32 v22, v36, v8
	v_cvt_pk_bf16_f32 v23, v34, v10
	global_store_dwordx4 v[26:27], v[22:25], off offset:2048
	v_cvt_pk_bf16_f32 v18, v14, v0
	v_cvt_pk_bf16_f32 v19, v20, v2
	v_cvt_pk_bf16_f32 v20, v16, v4
	v_cvt_pk_bf16_f32 v21, v17, v6
	global_store_dwordx4 v[26:27], v[18:21], off offset:2064
